# k61 + redundant s_waitcnt lgkmcnt(0) between the opening barrier and the first MFMA of each segment removed
# speedup vs baseline: 1.0043x; 1.0043x over previous
.LBB0_200:
	ds_read_b128 v[148:151], v169
	ds_read_b128 v[152:155], v169 offset:1024
	ds_read_b128 v[156:159], v169 offset:2048
	ds_read_b128 v[160:163], v169 offset:3072
	ds_read_b128 v[174:177], v170
	ds_read_b128 v[178:181], v170 offset:1024
	ds_read_b128 v[182:185], v170 offset:2048
	ds_read_b128 v[186:189], v170 offset:3072
	s_add_u32 s26, s6, 0xfff00800
	s_addc_u32 s27, s7, -1
	s_cmp_eq_u32 s34, 60
	s_cselect_b32 s29, s17, s27
	s_cselect_b32 s28, s23, s26
	s_cselect_b32 s27, s15, s31
	s_cselect_b32 s26, s25, s30
	v_lshl_add_u64 v[190:191], s[6:7], 0, v[138:139]
	s_add_i32 m0, s41, 0xc000
	s_nop 0
	global_load_lds_dwordx4 v[190:191], off
	v_lshl_add_u64 v[190:191], s[6:7], 0, v[140:141]
	s_add_i32 m0, s41, 0xe000
	s_nop 0
	global_load_lds_dwordx4 v[190:191], off
	ds_read_b128 v[190:193], v171
	ds_read_b128 v[194:197], v171 offset:1024
	ds_read_b128 v[198:201], v171 offset:2048
	ds_read_b128 v[202:205], v171 offset:3072
	ds_read_b128 v[206:209], v171 offset:4096
	ds_read_b128 v[210:213], v171 offset:5120
	ds_read_b128 v[214:217], v171 offset:6144
	ds_read_b128 v[218:221], v171 offset:7168
	s_waitcnt vmcnt(8)
	s_waitcnt lgkmcnt(0)
	s_barrier
	v_mfma_f32_16x16x32_bf16 v[124:127], v[148:151], v[190:193], v[124:127]
	v_mfma_f32_16x16x32_bf16 v[124:127], v[152:155], v[194:197], v[124:127]
	v_mfma_f32_16x16x32_bf16 v[120:123], v[160:163], v[194:197], v[120:123]
	v_mfma_f32_16x16x32_bf16 v[120:123], v[156:159], v[190:193], v[120:123]
	v_mfma_f32_16x16x32_bf16 v[60:63], v[174:177], v[190:193], v[60:63]
	v_mfma_f32_16x16x32_bf16 v[60:63], v[178:181], v[194:197], v[60:63]
	v_mfma_f32_16x16x32_bf16 v[56:59], v[186:189], v[194:197], v[56:59]
	v_mfma_f32_16x16x32_bf16 v[56:59], v[182:185], v[190:193], v[56:59]
	v_mfma_f32_16x16x32_bf16 v[48:51], v[182:185], v[198:201], v[48:51]
	v_mfma_f32_16x16x32_bf16 v[48:51], v[186:189], v[202:205], v[48:51]
	v_mfma_f32_16x16x32_bf16 v[52:55], v[178:181], v[202:205], v[52:55]
	v_mfma_f32_16x16x32_bf16 v[52:55], v[174:177], v[198:201], v[52:55]
	v_mfma_f32_16x16x32_bf16 v[112:115], v[156:159], v[198:201], v[112:115]
	v_mfma_f32_16x16x32_bf16 v[112:115], v[160:163], v[202:205], v[112:115]
	v_mfma_f32_16x16x32_bf16 v[116:119], v[152:155], v[202:205], v[116:119]
	v_mfma_f32_16x16x32_bf16 v[116:119], v[148:151], v[198:201], v[116:119]
	v_mfma_f32_16x16x32_bf16 v[108:111], v[148:151], v[206:209], v[108:111]
	v_mfma_f32_16x16x32_bf16 v[108:111], v[152:155], v[210:213], v[108:111]
	v_mfma_f32_16x16x32_bf16 v[104:107], v[160:163], v[210:213], v[104:107]
	v_mfma_f32_16x16x32_bf16 v[104:107], v[156:159], v[206:209], v[104:107]
	v_mfma_f32_16x16x32_bf16 v[44:47], v[174:177], v[206:209], v[44:47]
	v_mfma_f32_16x16x32_bf16 v[44:47], v[178:181], v[210:213], v[44:47]
	v_mfma_f32_16x16x32_bf16 v[40:43], v[186:189], v[210:213], v[40:43]
	v_mfma_f32_16x16x32_bf16 v[40:43], v[182:185], v[206:209], v[40:43]
	v_mfma_f32_16x16x32_bf16 v[32:35], v[182:185], v[214:217], v[32:35]
	v_mfma_f32_16x16x32_bf16 v[32:35], v[186:189], v[218:221], v[32:35]
	v_mfma_f32_16x16x32_bf16 v[36:39], v[178:181], v[218:221], v[36:39]
	v_mfma_f32_16x16x32_bf16 v[36:39], v[174:177], v[214:217], v[36:39]
	v_mfma_f32_16x16x32_bf16 v[96:99], v[156:159], v[214:217], v[96:99]
	v_mfma_f32_16x16x32_bf16 v[96:99], v[160:163], v[218:221], v[96:99]
	v_mfma_f32_16x16x32_bf16 v[100:103], v[152:155], v[218:221], v[100:103]
	v_mfma_f32_16x16x32_bf16 v[100:103], v[148:151], v[214:217], v[100:103]
	s_barrier
	s_add_i32 s35, s55, s36
	v_lshl_add_u64 v[222:223], s[26:27], 0, v[130:131]
	s_mov_b32 m0, s35
	v_lshl_add_u64 v[224:225], s[26:27], 0, v[134:135]
	global_load_lds_dwordx4 v[222:223], off
	s_add_i32 m0, s35, 0x2000
	s_add_u32 s58, s26, 0x100000
	s_addc_u32 s59, s27, 0
	s_add_i32 s35, s56, s36
	global_load_lds_dwordx4 v[224:225], off
	v_lshl_add_u64 v[190:191], s[58:59], 0, v[130:131]
	s_mov_b32 m0, s35
	v_lshl_add_u64 v[226:227], s[28:29], 0, v[128:129]
	global_load_lds_dwordx4 v[190:191], off
	v_lshl_add_u64 v[190:191], s[58:59], 0, v[134:135]
	s_add_i32 m0, s35, 0x2000
	v_lshl_add_u64 v[228:229], s[28:29], 0, v[132:133]
	global_load_lds_dwordx4 v[190:191], off
	s_mov_b32 m0, s41
	s_nop 0
	global_load_lds_dwordx4 v[226:227], off
	s_mov_b32 m0, s42
	s_nop 0
	global_load_lds_dwordx4 v[228:229], off
	ds_read_b128 v[190:193], v171 offset:16384
	ds_read_b128 v[194:197], v171 offset:17408
	ds_read_b128 v[198:201], v171 offset:18432
	ds_read_b128 v[202:205], v171 offset:19456
	ds_read_b128 v[206:209], v171 offset:20480
	ds_read_b128 v[210:213], v171 offset:21504
	ds_read_b128 v[214:217], v171 offset:22528
	ds_read_b128 v[218:221], v171 offset:23552
	s_waitcnt vmcnt(8)
	s_waitcnt lgkmcnt(0)
	s_barrier
	v_mfma_f32_16x16x32_bf16 v[92:95], v[148:151], v[190:193], v[92:95]
	v_mfma_f32_16x16x32_bf16 v[92:95], v[152:155], v[194:197], v[92:95]
	v_mfma_f32_16x16x32_bf16 v[88:91], v[160:163], v[194:197], v[88:91]
	v_mfma_f32_16x16x32_bf16 v[88:91], v[156:159], v[190:193], v[88:91]
	v_mfma_f32_16x16x32_bf16 v[28:31], v[174:177], v[190:193], v[28:31]
	v_mfma_f32_16x16x32_bf16 v[28:31], v[178:181], v[194:197], v[28:31]
	v_mfma_f32_16x16x32_bf16 v[24:27], v[186:189], v[194:197], v[24:27]
	v_mfma_f32_16x16x32_bf16 v[24:27], v[182:185], v[190:193], v[24:27]
	v_mfma_f32_16x16x32_bf16 v[16:19], v[182:185], v[198:201], v[16:19]
	v_mfma_f32_16x16x32_bf16 v[16:19], v[186:189], v[202:205], v[16:19]
	v_mfma_f32_16x16x32_bf16 v[20:23], v[178:181], v[202:205], v[20:23]
	v_mfma_f32_16x16x32_bf16 v[20:23], v[174:177], v[198:201], v[20:23]
	v_mfma_f32_16x16x32_bf16 v[80:83], v[156:159], v[198:201], v[80:83]
	v_mfma_f32_16x16x32_bf16 v[80:83], v[160:163], v[202:205], v[80:83]
	v_mfma_f32_16x16x32_bf16 v[84:87], v[152:155], v[202:205], v[84:87]
	v_mfma_f32_16x16x32_bf16 v[84:87], v[148:151], v[198:201], v[84:87]
	v_mfma_f32_16x16x32_bf16 v[76:79], v[148:151], v[206:209], v[76:79]
	v_mfma_f32_16x16x32_bf16 v[76:79], v[152:155], v[210:213], v[76:79]
	v_mfma_f32_16x16x32_bf16 v[72:75], v[160:163], v[210:213], v[72:75]
	v_mfma_f32_16x16x32_bf16 v[72:75], v[156:159], v[206:209], v[72:75]
	v_mfma_f32_16x16x32_bf16 v[12:15], v[174:177], v[206:209], v[12:15]
	v_mfma_f32_16x16x32_bf16 v[12:15], v[178:181], v[210:213], v[12:15]
	v_mfma_f32_16x16x32_bf16 v[8:11], v[186:189], v[210:213], v[8:11]
	v_mfma_f32_16x16x32_bf16 v[8:11], v[182:185], v[206:209], v[8:11]
	v_mfma_f32_16x16x32_bf16 v[0:3], v[182:185], v[214:217], v[0:3]
	v_mfma_f32_16x16x32_bf16 v[0:3], v[186:189], v[218:221], v[0:3]
	v_mfma_f32_16x16x32_bf16 v[4:7], v[178:181], v[218:221], v[4:7]
	v_mfma_f32_16x16x32_bf16 v[4:7], v[174:177], v[214:217], v[4:7]
	v_mfma_f32_16x16x32_bf16 v[64:67], v[156:159], v[214:217], v[64:67]
	v_mfma_f32_16x16x32_bf16 v[64:67], v[160:163], v[218:221], v[64:67]
	v_mfma_f32_16x16x32_bf16 v[68:71], v[152:155], v[218:221], v[68:71]
	v_mfma_f32_16x16x32_bf16 v[68:71], v[148:151], v[214:217], v[68:71]
	s_barrier
	s_add_i32 s35, 0, 0x18000
	v_add_u32_e32 v136, s35, v165
	s_add_i32 s57, 0, 0x1c000
	ds_read_b128 v[148:151], v136
	ds_read_b128 v[152:155], v136 offset:1024
	ds_read_b128 v[156:159], v136 offset:2048
	ds_read_b128 v[160:163], v136 offset:3072
	v_add_u32_e32 v136, s57, v165
	ds_read_b128 v[174:177], v136
	ds_read_b128 v[178:181], v136 offset:1024
	ds_read_b128 v[182:185], v136 offset:2048
	ds_read_b128 v[186:189], v136 offset:3072
	s_add_u32 s28, s28, 0x100000
	s_addc_u32 s29, s29, 0
	s_mov_b32 m0, s43
	v_lshl_add_u64 v[190:191], s[28:29], 0, v[128:129]
	global_load_lds_dwordx4 v[190:191], off
	v_lshl_add_u64 v[190:191], s[28:29], 0, v[132:133]
	s_mov_b32 m0, s44
	s_nop 0
	global_load_lds_dwordx4 v[190:191], off
	ds_read_b128 v[190:193], v171 offset:32768
	ds_read_b128 v[194:197], v171 offset:33792
	ds_read_b128 v[198:201], v171 offset:34816
	ds_read_b128 v[202:205], v171 offset:35840
	ds_read_b128 v[206:209], v171 offset:36864
	ds_read_b128 v[210:213], v171 offset:37888
	ds_read_b128 v[214:217], v171 offset:38912
	ds_read_b128 v[218:221], v171 offset:39936
	s_waitcnt vmcnt(8)
	s_waitcnt lgkmcnt(0)
	s_barrier
	v_mfma_f32_16x16x32_bf16 v[124:127], v[148:151], v[190:193], v[124:127]
	v_mfma_f32_16x16x32_bf16 v[124:127], v[152:155], v[194:197], v[124:127]
	v_mfma_f32_16x16x32_bf16 v[120:123], v[160:163], v[194:197], v[120:123]
	v_mfma_f32_16x16x32_bf16 v[120:123], v[156:159], v[190:193], v[120:123]
	v_mfma_f32_16x16x32_bf16 v[60:63], v[174:177], v[190:193], v[60:63]
	v_mfma_f32_16x16x32_bf16 v[60:63], v[178:181], v[194:197], v[60:63]
	v_mfma_f32_16x16x32_bf16 v[56:59], v[186:189], v[194:197], v[56:59]
	v_mfma_f32_16x16x32_bf16 v[56:59], v[182:185], v[190:193], v[56:59]
	v_mfma_f32_16x16x32_bf16 v[48:51], v[182:185], v[198:201], v[48:51]
	v_mfma_f32_16x16x32_bf16 v[48:51], v[186:189], v[202:205], v[48:51]
	v_mfma_f32_16x16x32_bf16 v[52:55], v[178:181], v[202:205], v[52:55]
	v_mfma_f32_16x16x32_bf16 v[52:55], v[174:177], v[198:201], v[52:55]
	v_mfma_f32_16x16x32_bf16 v[112:115], v[156:159], v[198:201], v[112:115]
	v_mfma_f32_16x16x32_bf16 v[112:115], v[160:163], v[202:205], v[112:115]
	v_mfma_f32_16x16x32_bf16 v[116:119], v[152:155], v[202:205], v[116:119]
	v_mfma_f32_16x16x32_bf16 v[116:119], v[148:151], v[198:201], v[116:119]
	v_mfma_f32_16x16x32_bf16 v[108:111], v[148:151], v[206:209], v[108:111]
	v_mfma_f32_16x16x32_bf16 v[108:111], v[152:155], v[210:213], v[108:111]
	v_mfma_f32_16x16x32_bf16 v[104:107], v[160:163], v[210:213], v[104:107]
	v_mfma_f32_16x16x32_bf16 v[104:107], v[156:159], v[206:209], v[104:107]
	v_mfma_f32_16x16x32_bf16 v[44:47], v[174:177], v[206:209], v[44:47]
	v_mfma_f32_16x16x32_bf16 v[44:47], v[178:181], v[210:213], v[44:47]
	v_mfma_f32_16x16x32_bf16 v[40:43], v[186:189], v[210:213], v[40:43]
	v_mfma_f32_16x16x32_bf16 v[40:43], v[182:185], v[206:209], v[40:43]
	v_mfma_f32_16x16x32_bf16 v[32:35], v[182:185], v[214:217], v[32:35]
	v_mfma_f32_16x16x32_bf16 v[32:35], v[186:189], v[218:221], v[32:35]
	v_mfma_f32_16x16x32_bf16 v[36:39], v[178:181], v[218:221], v[36:39]
	v_mfma_f32_16x16x32_bf16 v[36:39], v[174:177], v[214:217], v[36:39]
	v_mfma_f32_16x16x32_bf16 v[96:99], v[156:159], v[214:217], v[96:99]
	v_mfma_f32_16x16x32_bf16 v[96:99], v[160:163], v[218:221], v[96:99]
	v_mfma_f32_16x16x32_bf16 v[100:103], v[152:155], v[218:221], v[100:103]
	v_mfma_f32_16x16x32_bf16 v[100:103], v[148:151], v[214:217], v[100:103]
	s_barrier
	s_add_i32 s28, s35, s36
	v_lshl_add_u64 v[190:191], v[222:223], 0, s[12:13]
	s_mov_b32 m0, s28
	s_nop 0
	global_load_lds_dwordx4 v[190:191], off
	s_add_i32 m0, s28, 0x2000
	s_add_u32 s26, s26, 0x100800
	v_lshl_add_u64 v[190:191], v[224:225], 0, s[12:13]
	s_addc_u32 s27, s27, 0
	s_add_i32 s28, s57, s36
	global_load_lds_dwordx4 v[190:191], off
	v_lshl_add_u64 v[190:191], s[26:27], 0, v[130:131]
	s_mov_b32 m0, s28
	s_nop 0
	global_load_lds_dwordx4 v[190:191], off
	v_lshl_add_u64 v[190:191], s[26:27], 0, v[134:135]
	s_add_i32 m0, s28, 0x2000
	s_nop 0
	global_load_lds_dwordx4 v[190:191], off
	v_lshl_add_u64 v[190:191], v[226:227], 0, s[12:13]
	s_mov_b32 m0, s49
	s_nop 0
	global_load_lds_dwordx4 v[190:191], off
	v_lshl_add_u64 v[190:191], v[228:229], 0, s[12:13]
	s_mov_b32 m0, s50
	s_nop 0
	global_load_lds_dwordx4 v[190:191], off
	ds_read_b128 v[190:193], v171 offset:49152
	ds_read_b128 v[194:197], v171 offset:50176
	ds_read_b128 v[198:201], v171 offset:51200
	ds_read_b128 v[202:205], v171 offset:52224
	ds_read_b128 v[206:209], v171 offset:53248
	ds_read_b128 v[210:213], v171 offset:54272
	ds_read_b128 v[214:217], v171 offset:55296
	ds_read_b128 v[218:221], v171 offset:56320
	s_waitcnt vmcnt(8)
	s_waitcnt lgkmcnt(0)
	s_barrier
	v_mfma_f32_16x16x32_bf16 v[92:95], v[148:151], v[190:193], v[92:95]
	v_mfma_f32_16x16x32_bf16 v[92:95], v[152:155], v[194:197], v[92:95]
	v_mfma_f32_16x16x32_bf16 v[88:91], v[160:163], v[194:197], v[88:91]
	v_mfma_f32_16x16x32_bf16 v[88:91], v[156:159], v[190:193], v[88:91]
	v_mfma_f32_16x16x32_bf16 v[28:31], v[174:177], v[190:193], v[28:31]
	v_mfma_f32_16x16x32_bf16 v[28:31], v[178:181], v[194:197], v[28:31]
	v_mfma_f32_16x16x32_bf16 v[24:27], v[186:189], v[194:197], v[24:27]
	v_mfma_f32_16x16x32_bf16 v[24:27], v[182:185], v[190:193], v[24:27]
	v_mfma_f32_16x16x32_bf16 v[16:19], v[182:185], v[198:201], v[16:19]
	v_mfma_f32_16x16x32_bf16 v[16:19], v[186:189], v[202:205], v[16:19]
	v_mfma_f32_16x16x32_bf16 v[20:23], v[178:181], v[202:205], v[20:23]
	v_mfma_f32_16x16x32_bf16 v[20:23], v[174:177], v[198:201], v[20:23]
	v_mfma_f32_16x16x32_bf16 v[80:83], v[156:159], v[198:201], v[80:83]
	v_mfma_f32_16x16x32_bf16 v[80:83], v[160:163], v[202:205], v[80:83]
	v_mfma_f32_16x16x32_bf16 v[84:87], v[152:155], v[202:205], v[84:87]
	v_mfma_f32_16x16x32_bf16 v[84:87], v[148:151], v[198:201], v[84:87]
	v_mfma_f32_16x16x32_bf16 v[76:79], v[148:151], v[206:209], v[76:79]
	v_mfma_f32_16x16x32_bf16 v[76:79], v[152:155], v[210:213], v[76:79]
	v_mfma_f32_16x16x32_bf16 v[72:75], v[160:163], v[210:213], v[72:75]
	v_mfma_f32_16x16x32_bf16 v[72:75], v[156:159], v[206:209], v[72:75]
	v_mfma_f32_16x16x32_bf16 v[12:15], v[174:177], v[206:209], v[12:15]
	v_mfma_f32_16x16x32_bf16 v[12:15], v[178:181], v[210:213], v[12:15]
	v_mfma_f32_16x16x32_bf16 v[8:11], v[186:189], v[210:213], v[8:11]
	v_mfma_f32_16x16x32_bf16 v[8:11], v[182:185], v[206:209], v[8:11]
	v_mfma_f32_16x16x32_bf16 v[0:3], v[182:185], v[214:217], v[0:3]
	v_mfma_f32_16x16x32_bf16 v[0:3], v[186:189], v[218:221], v[0:3]
	v_mfma_f32_16x16x32_bf16 v[4:7], v[178:181], v[218:221], v[4:7]
	v_mfma_f32_16x16x32_bf16 v[4:7], v[174:177], v[214:217], v[4:7]
	v_mfma_f32_16x16x32_bf16 v[64:67], v[156:159], v[214:217], v[64:67]
	v_mfma_f32_16x16x32_bf16 v[64:67], v[160:163], v[218:221], v[64:67]
	v_mfma_f32_16x16x32_bf16 v[68:71], v[152:155], v[218:221], v[68:71]
	v_mfma_f32_16x16x32_bf16 v[68:71], v[148:151], v[214:217], v[68:71]
	s_barrier
	s_add_i32 s34, s34, 2
	s_add_u32 s6, s6, 0x1000
	s_addc_u32 s7, s7, 0
	s_add_u32 s30, s30, 0x1000
	s_addc_u32 s31, s31, 0
	s_cmp_gt_u32 s34, 61
	s_cbranch_scc0 .LBB0_200

.LBB0_333:
	ds_read_b128 v[144:147], v152
	ds_read_b128 v[156:159], v152 offset:1024
	ds_read_b128 v[160:163], v152 offset:2048
	ds_read_b128 v[164:167], v152 offset:3072
	ds_read_b128 v[168:171], v153
	ds_read_b128 v[172:175], v153 offset:1024
	ds_read_b128 v[176:179], v153 offset:2048
	ds_read_b128 v[180:183], v153 offset:3072
	s_add_u32 s28, s24, 0x100
	s_addc_u32 s29, s25, 0
	s_cmp_eq_u32 s56, 60
	s_cselect_b32 s35, s13, s29
	s_cselect_b32 s34, s52, s28
	s_cselect_b32 s31, s11, s55
	s_cselect_b32 s30, s53, s54
	v_lshl_add_u64 v[184:185], s[24:25], 0, v[136:137]
	s_add_i32 m0, s21, 0xc000
	s_nop 0
	global_load_lds_dwordx4 v[184:185], off
	v_lshl_add_u64 v[184:185], s[24:25], 0, v[138:139]
	s_add_i32 m0, s21, 0xe000
	s_nop 0
	global_load_lds_dwordx4 v[184:185], off
	ds_read_b128 v[184:187], v154
	ds_read_b128 v[188:191], v154 offset:1024
	ds_read_b128 v[192:195], v154 offset:2048
	ds_read_b128 v[196:199], v154 offset:3072
	ds_read_b128 v[200:203], v154 offset:4096
	ds_read_b128 v[204:207], v154 offset:5120
	ds_read_b128 v[208:211], v154 offset:6144
	ds_read_b128 v[212:215], v154 offset:7168
	s_waitcnt vmcnt(8)
	s_waitcnt lgkmcnt(0)
	s_barrier
	v_mfma_f32_16x16x32_bf16 v[124:127], v[144:147], v[184:187], v[124:127]
	v_mfma_f32_16x16x32_bf16 v[124:127], v[156:159], v[188:191], v[124:127]
	v_mfma_f32_16x16x32_bf16 v[120:123], v[164:167], v[188:191], v[120:123]
	v_mfma_f32_16x16x32_bf16 v[120:123], v[160:163], v[184:187], v[120:123]
	v_mfma_f32_16x16x32_bf16 v[112:115], v[168:171], v[184:187], v[112:115]
	v_mfma_f32_16x16x32_bf16 v[112:115], v[172:175], v[188:191], v[112:115]
	v_mfma_f32_16x16x32_bf16 v[104:107], v[180:183], v[188:191], v[104:107]
	v_mfma_f32_16x16x32_bf16 v[104:107], v[176:179], v[184:187], v[104:107]
	v_mfma_f32_16x16x32_bf16 v[88:91], v[176:179], v[192:195], v[88:91]
	v_mfma_f32_16x16x32_bf16 v[88:91], v[180:183], v[196:199], v[88:91]
	v_mfma_f32_16x16x32_bf16 v[96:99], v[172:175], v[196:199], v[96:99]
	v_mfma_f32_16x16x32_bf16 v[96:99], v[168:171], v[192:195], v[96:99]
	v_mfma_f32_16x16x32_bf16 v[108:111], v[160:163], v[192:195], v[108:111]
	v_mfma_f32_16x16x32_bf16 v[108:111], v[164:167], v[196:199], v[108:111]
	v_mfma_f32_16x16x32_bf16 v[116:119], v[156:159], v[196:199], v[116:119]
	v_mfma_f32_16x16x32_bf16 v[116:119], v[144:147], v[192:195], v[116:119]
	v_mfma_f32_16x16x32_bf16 v[100:103], v[144:147], v[200:203], v[100:103]
	v_mfma_f32_16x16x32_bf16 v[100:103], v[156:159], v[204:207], v[100:103]
	v_mfma_f32_16x16x32_bf16 v[92:95], v[164:167], v[204:207], v[92:95]
	v_mfma_f32_16x16x32_bf16 v[92:95], v[160:163], v[200:203], v[92:95]
	v_mfma_f32_16x16x32_bf16 v[80:83], v[168:171], v[200:203], v[80:83]
	v_mfma_f32_16x16x32_bf16 v[80:83], v[172:175], v[204:207], v[80:83]
	v_mfma_f32_16x16x32_bf16 v[72:75], v[180:183], v[204:207], v[72:75]
	v_mfma_f32_16x16x32_bf16 v[72:75], v[176:179], v[200:203], v[72:75]
	v_mfma_f32_16x16x32_bf16 v[64:67], v[176:179], v[208:211], v[64:67]
	v_mfma_f32_16x16x32_bf16 v[64:67], v[180:183], v[212:215], v[64:67]
	v_mfma_f32_16x16x32_bf16 v[68:71], v[172:175], v[212:215], v[68:71]
	v_mfma_f32_16x16x32_bf16 v[68:71], v[168:171], v[208:211], v[68:71]
	v_mfma_f32_16x16x32_bf16 v[76:79], v[160:163], v[208:211], v[76:79]
	v_mfma_f32_16x16x32_bf16 v[76:79], v[164:167], v[212:215], v[76:79]
	v_mfma_f32_16x16x32_bf16 v[84:87], v[156:159], v[212:215], v[84:87]
	v_mfma_f32_16x16x32_bf16 v[84:87], v[144:147], v[208:211], v[84:87]
	s_barrier
	s_add_i32 s24, s49, s41
	v_lshl_add_u64 v[216:217], s[30:31], 0, v[130:131]
	s_mov_b32 m0, s24
	v_lshl_add_u64 v[218:219], s[30:31], 0, v[134:135]
	global_load_lds_dwordx4 v[216:217], off
	s_add_i32 m0, s24, 0x2000
	s_add_u32 s24, s30, 0x100000
	s_addc_u32 s25, s31, 0
	s_add_i32 s57, s50, s41
	global_load_lds_dwordx4 v[218:219], off
	v_lshl_add_u64 v[184:185], s[24:25], 0, v[130:131]
	s_mov_b32 m0, s57
	v_lshl_add_u64 v[220:221], s[34:35], 0, v[128:129]
	global_load_lds_dwordx4 v[184:185], off
	v_lshl_add_u64 v[184:185], s[24:25], 0, v[134:135]
	s_add_i32 m0, s57, 0x2000
	v_lshl_add_u64 v[222:223], s[34:35], 0, v[132:133]
	global_load_lds_dwordx4 v[184:185], off
	s_mov_b32 m0, s21
	s_nop 0
	global_load_lds_dwordx4 v[220:221], off
	s_mov_b32 m0, s42
	s_nop 0
	global_load_lds_dwordx4 v[222:223], off
	ds_read_b128 v[184:187], v154 offset:16384
	ds_read_b128 v[188:191], v154 offset:17408
	ds_read_b128 v[192:195], v154 offset:18432
	ds_read_b128 v[196:199], v154 offset:19456
	ds_read_b128 v[200:203], v154 offset:20480
	ds_read_b128 v[204:207], v154 offset:21504
	ds_read_b128 v[208:211], v154 offset:22528
	ds_read_b128 v[212:215], v154 offset:23552
	s_waitcnt vmcnt(8)
	s_waitcnt lgkmcnt(0)
	s_barrier
	v_mfma_f32_16x16x32_bf16 v[60:63], v[144:147], v[184:187], v[60:63]
	v_mfma_f32_16x16x32_bf16 v[60:63], v[156:159], v[188:191], v[60:63]
	v_mfma_f32_16x16x32_bf16 v[56:59], v[164:167], v[188:191], v[56:59]
	v_mfma_f32_16x16x32_bf16 v[56:59], v[160:163], v[184:187], v[56:59]
	v_mfma_f32_16x16x32_bf16 v[48:51], v[168:171], v[184:187], v[48:51]
	v_mfma_f32_16x16x32_bf16 v[48:51], v[172:175], v[188:191], v[48:51]
	v_mfma_f32_16x16x32_bf16 v[40:43], v[180:183], v[188:191], v[40:43]
	v_mfma_f32_16x16x32_bf16 v[40:43], v[176:179], v[184:187], v[40:43]
	v_mfma_f32_16x16x32_bf16 v[24:27], v[176:179], v[192:195], v[24:27]
	v_mfma_f32_16x16x32_bf16 v[24:27], v[180:183], v[196:199], v[24:27]
	v_mfma_f32_16x16x32_bf16 v[32:35], v[172:175], v[196:199], v[32:35]
	v_mfma_f32_16x16x32_bf16 v[32:35], v[168:171], v[192:195], v[32:35]
	v_mfma_f32_16x16x32_bf16 v[44:47], v[160:163], v[192:195], v[44:47]
	v_mfma_f32_16x16x32_bf16 v[44:47], v[164:167], v[196:199], v[44:47]
	v_mfma_f32_16x16x32_bf16 v[52:55], v[156:159], v[196:199], v[52:55]
	v_mfma_f32_16x16x32_bf16 v[52:55], v[144:147], v[192:195], v[52:55]
	v_mfma_f32_16x16x32_bf16 v[36:39], v[144:147], v[200:203], v[36:39]
	v_mfma_f32_16x16x32_bf16 v[36:39], v[156:159], v[204:207], v[36:39]
	v_mfma_f32_16x16x32_bf16 v[28:31], v[164:167], v[204:207], v[28:31]
	v_mfma_f32_16x16x32_bf16 v[28:31], v[160:163], v[200:203], v[28:31]
	v_mfma_f32_16x16x32_bf16 v[16:19], v[168:171], v[200:203], v[16:19]
	v_mfma_f32_16x16x32_bf16 v[16:19], v[172:175], v[204:207], v[16:19]
	v_mfma_f32_16x16x32_bf16 v[8:11], v[180:183], v[204:207], v[8:11]
	v_mfma_f32_16x16x32_bf16 v[8:11], v[176:179], v[200:203], v[8:11]
	v_mfma_f32_16x16x32_bf16 v[0:3], v[176:179], v[208:211], v[0:3]
	v_mfma_f32_16x16x32_bf16 v[0:3], v[180:183], v[212:215], v[0:3]
	v_mfma_f32_16x16x32_bf16 v[4:7], v[172:175], v[212:215], v[4:7]
	v_mfma_f32_16x16x32_bf16 v[4:7], v[168:171], v[208:211], v[4:7]
	v_mfma_f32_16x16x32_bf16 v[12:15], v[160:163], v[208:211], v[12:15]
	v_mfma_f32_16x16x32_bf16 v[12:15], v[164:167], v[212:215], v[12:15]
	v_mfma_f32_16x16x32_bf16 v[20:23], v[156:159], v[212:215], v[20:23]
	v_mfma_f32_16x16x32_bf16 v[20:23], v[144:147], v[208:211], v[20:23]
	s_barrier
	s_add_i32 s57, 0, 0x18000
	v_add_u32_e32 v155, s57, v149
	s_add_i32 s58, 0, 0x1c000
	ds_read_b128 v[144:147], v155
	ds_read_b128 v[156:159], v155 offset:1024
	ds_read_b128 v[160:163], v155 offset:2048
	ds_read_b128 v[164:167], v155 offset:3072
	v_add_u32_e32 v155, s58, v149
	ds_read_b128 v[168:171], v155
	ds_read_b128 v[172:175], v155 offset:1024
	ds_read_b128 v[176:179], v155 offset:2048
	ds_read_b128 v[180:183], v155 offset:3072
	s_add_u32 s24, s34, 0x100000
	s_addc_u32 s25, s35, 0
	s_mov_b32 m0, s43
	v_lshl_add_u64 v[184:185], s[24:25], 0, v[128:129]
	global_load_lds_dwordx4 v[184:185], off
	v_lshl_add_u64 v[184:185], s[24:25], 0, v[132:133]
	s_mov_b32 m0, s44
	s_nop 0
	global_load_lds_dwordx4 v[184:185], off
	ds_read_b128 v[184:187], v154 offset:32768
	ds_read_b128 v[188:191], v154 offset:33792
	ds_read_b128 v[192:195], v154 offset:34816
	ds_read_b128 v[196:199], v154 offset:35840
	ds_read_b128 v[200:203], v154 offset:36864
	ds_read_b128 v[204:207], v154 offset:37888
	ds_read_b128 v[208:211], v154 offset:38912
	ds_read_b128 v[212:215], v154 offset:39936
	s_waitcnt vmcnt(8)
	s_waitcnt lgkmcnt(0)
	s_barrier
	v_mfma_f32_16x16x32_bf16 v[124:127], v[144:147], v[184:187], v[124:127]
	v_mfma_f32_16x16x32_bf16 v[124:127], v[156:159], v[188:191], v[124:127]
	v_mfma_f32_16x16x32_bf16 v[120:123], v[164:167], v[188:191], v[120:123]
	v_mfma_f32_16x16x32_bf16 v[120:123], v[160:163], v[184:187], v[120:123]
	v_mfma_f32_16x16x32_bf16 v[112:115], v[168:171], v[184:187], v[112:115]
	v_mfma_f32_16x16x32_bf16 v[112:115], v[172:175], v[188:191], v[112:115]
	v_mfma_f32_16x16x32_bf16 v[104:107], v[180:183], v[188:191], v[104:107]
	v_mfma_f32_16x16x32_bf16 v[104:107], v[176:179], v[184:187], v[104:107]
	v_mfma_f32_16x16x32_bf16 v[88:91], v[176:179], v[192:195], v[88:91]
	v_mfma_f32_16x16x32_bf16 v[88:91], v[180:183], v[196:199], v[88:91]
	v_mfma_f32_16x16x32_bf16 v[96:99], v[172:175], v[196:199], v[96:99]
	v_mfma_f32_16x16x32_bf16 v[96:99], v[168:171], v[192:195], v[96:99]
	v_mfma_f32_16x16x32_bf16 v[108:111], v[160:163], v[192:195], v[108:111]
	v_mfma_f32_16x16x32_bf16 v[108:111], v[164:167], v[196:199], v[108:111]
	v_mfma_f32_16x16x32_bf16 v[116:119], v[156:159], v[196:199], v[116:119]
	v_mfma_f32_16x16x32_bf16 v[116:119], v[144:147], v[192:195], v[116:119]
	v_mfma_f32_16x16x32_bf16 v[100:103], v[144:147], v[200:203], v[100:103]
	v_mfma_f32_16x16x32_bf16 v[100:103], v[156:159], v[204:207], v[100:103]
	v_mfma_f32_16x16x32_bf16 v[92:95], v[164:167], v[204:207], v[92:95]
	v_mfma_f32_16x16x32_bf16 v[92:95], v[160:163], v[200:203], v[92:95]
	v_mfma_f32_16x16x32_bf16 v[80:83], v[168:171], v[200:203], v[80:83]
	v_mfma_f32_16x16x32_bf16 v[80:83], v[172:175], v[204:207], v[80:83]
	v_mfma_f32_16x16x32_bf16 v[72:75], v[180:183], v[204:207], v[72:75]
	v_mfma_f32_16x16x32_bf16 v[72:75], v[176:179], v[200:203], v[72:75]
	v_mfma_f32_16x16x32_bf16 v[64:67], v[176:179], v[208:211], v[64:67]
	v_mfma_f32_16x16x32_bf16 v[64:67], v[180:183], v[212:215], v[64:67]
	v_mfma_f32_16x16x32_bf16 v[68:71], v[172:175], v[212:215], v[68:71]
	v_mfma_f32_16x16x32_bf16 v[68:71], v[168:171], v[208:211], v[68:71]
	v_mfma_f32_16x16x32_bf16 v[76:79], v[160:163], v[208:211], v[76:79]
	v_mfma_f32_16x16x32_bf16 v[76:79], v[164:167], v[212:215], v[76:79]
	v_mfma_f32_16x16x32_bf16 v[84:87], v[156:159], v[212:215], v[84:87]
	v_mfma_f32_16x16x32_bf16 v[84:87], v[144:147], v[208:211], v[84:87]
	s_barrier
	s_add_i32 s24, s57, s41
	v_lshl_add_u64 v[184:185], v[216:217], 0, s[8:9]
	s_mov_b32 m0, s24
	s_nop 0
	global_load_lds_dwordx4 v[184:185], off
	s_add_i32 m0, s24, 0x2000
	s_add_u32 s24, s30, 0x100080
	v_lshl_add_u64 v[184:185], v[218:219], 0, s[8:9]
	s_addc_u32 s25, s31, 0
	s_add_i32 s30, s58, s41
	global_load_lds_dwordx4 v[184:185], off
	v_lshl_add_u64 v[184:185], s[24:25], 0, v[130:131]
	s_mov_b32 m0, s30
	s_nop 0
	global_load_lds_dwordx4 v[184:185], off
	v_lshl_add_u64 v[184:185], s[24:25], 0, v[134:135]
	s_add_i32 m0, s30, 0x2000
	s_nop 0
	global_load_lds_dwordx4 v[184:185], off
	v_lshl_add_u64 v[184:185], v[220:221], 0, s[8:9]
	s_mov_b32 m0, s46
	s_nop 0
	global_load_lds_dwordx4 v[184:185], off
	v_lshl_add_u64 v[184:185], v[222:223], 0, s[8:9]
	s_mov_b32 m0, s47
	s_nop 0
	global_load_lds_dwordx4 v[184:185], off
	ds_read_b128 v[184:187], v154 offset:49152
	ds_read_b128 v[188:191], v154 offset:50176
	ds_read_b128 v[192:195], v154 offset:51200
	ds_read_b128 v[196:199], v154 offset:52224
	ds_read_b128 v[200:203], v154 offset:53248
	ds_read_b128 v[204:207], v154 offset:54272
	ds_read_b128 v[208:211], v154 offset:55296
	ds_read_b128 v[212:215], v154 offset:56320
	s_waitcnt vmcnt(8)
	s_waitcnt lgkmcnt(0)
	s_barrier
	v_mfma_f32_16x16x32_bf16 v[60:63], v[144:147], v[184:187], v[60:63]
	v_mfma_f32_16x16x32_bf16 v[60:63], v[156:159], v[188:191], v[60:63]
	v_mfma_f32_16x16x32_bf16 v[56:59], v[164:167], v[188:191], v[56:59]
	v_mfma_f32_16x16x32_bf16 v[56:59], v[160:163], v[184:187], v[56:59]
	v_mfma_f32_16x16x32_bf16 v[48:51], v[168:171], v[184:187], v[48:51]
	v_mfma_f32_16x16x32_bf16 v[48:51], v[172:175], v[188:191], v[48:51]
	v_mfma_f32_16x16x32_bf16 v[40:43], v[180:183], v[188:191], v[40:43]
	v_mfma_f32_16x16x32_bf16 v[40:43], v[176:179], v[184:187], v[40:43]
	v_mfma_f32_16x16x32_bf16 v[24:27], v[176:179], v[192:195], v[24:27]
	v_mfma_f32_16x16x32_bf16 v[24:27], v[180:183], v[196:199], v[24:27]
	v_mfma_f32_16x16x32_bf16 v[32:35], v[172:175], v[196:199], v[32:35]
	v_mfma_f32_16x16x32_bf16 v[32:35], v[168:171], v[192:195], v[32:35]
	v_mfma_f32_16x16x32_bf16 v[44:47], v[160:163], v[192:195], v[44:47]
	v_mfma_f32_16x16x32_bf16 v[44:47], v[164:167], v[196:199], v[44:47]
	v_mfma_f32_16x16x32_bf16 v[52:55], v[156:159], v[196:199], v[52:55]
	v_mfma_f32_16x16x32_bf16 v[52:55], v[144:147], v[192:195], v[52:55]
	v_mfma_f32_16x16x32_bf16 v[36:39], v[144:147], v[200:203], v[36:39]
	v_mfma_f32_16x16x32_bf16 v[36:39], v[156:159], v[204:207], v[36:39]
	v_mfma_f32_16x16x32_bf16 v[28:31], v[164:167], v[204:207], v[28:31]
	v_mfma_f32_16x16x32_bf16 v[28:31], v[160:163], v[200:203], v[28:31]
	v_mfma_f32_16x16x32_bf16 v[16:19], v[168:171], v[200:203], v[16:19]
	v_mfma_f32_16x16x32_bf16 v[16:19], v[172:175], v[204:207], v[16:19]
	v_mfma_f32_16x16x32_bf16 v[8:11], v[180:183], v[204:207], v[8:11]
	v_mfma_f32_16x16x32_bf16 v[8:11], v[176:179], v[200:203], v[8:11]
	v_mfma_f32_16x16x32_bf16 v[0:3], v[176:179], v[208:211], v[0:3]
	v_mfma_f32_16x16x32_bf16 v[0:3], v[180:183], v[212:215], v[0:3]
	v_mfma_f32_16x16x32_bf16 v[4:7], v[172:175], v[212:215], v[4:7]
	v_mfma_f32_16x16x32_bf16 v[4:7], v[168:171], v[208:211], v[4:7]
	v_mfma_f32_16x16x32_bf16 v[12:15], v[160:163], v[208:211], v[12:15]
	v_mfma_f32_16x16x32_bf16 v[12:15], v[164:167], v[212:215], v[12:15]
	v_mfma_f32_16x16x32_bf16 v[20:23], v[156:159], v[212:215], v[20:23]
	v_mfma_f32_16x16x32_bf16 v[20:23], v[144:147], v[208:211], v[20:23]
	s_barrier
	s_add_i32 s56, s56, 2
	s_add_u32 s54, s54, 0x100
	s_addc_u32 s55, s55, 0
	s_cmp_gt_u32 s56, 61
	s_mov_b64 s[24:25], s[28:29]
	s_cbranch_scc0 .LBB0_333
	s_and_b64 vcc, exec, s[0:1]
	s_cbranch_vccz .LBB0_336
	s_barrier

.LBB0_1202:
	ds_read_b128 v[128:131], v176
	ds_read_b128 v[132:135], v176 offset:1024
	ds_read_b128 v[136:139], v176 offset:2048
	ds_read_b128 v[140:143], v176 offset:3072
	ds_read_b128 v[144:147], v177
	ds_read_b128 v[148:151], v177 offset:1024
	ds_read_b128 v[180:183], v177 offset:2048
	ds_read_b128 v[184:187], v177 offset:3072
	s_add_u32 s30, s28, 0xfff00080
	s_addc_u32 s31, s29, -1
	s_cmp_eq_u32 s40, 60
	s_cselect_b32 s35, s23, s31
	s_cselect_b32 s34, s36, s30
	s_cselect_b32 s31, s21, s39
	s_cselect_b32 s30, s37, s38
	v_lshl_add_u64 v[172:173], s[28:29], 0, v[164:165]
	s_add_i32 m0, s7, 0xc000
	s_nop 0
	global_load_lds_dwordx4 v[172:173], off
	v_lshl_add_u64 v[172:173], s[28:29], 0, v[166:167]
	s_add_i32 m0, s7, 0xe000
	s_nop 0
	global_load_lds_dwordx4 v[172:173], off
	ds_read_b128 v[188:191], v178
	ds_read_b128 v[192:195], v178 offset:1024
	ds_read_b128 v[196:199], v178 offset:2048
	ds_read_b128 v[200:203], v178 offset:3072
	ds_read_b128 v[204:207], v178 offset:4096
	ds_read_b128 v[208:211], v178 offset:5120
	ds_read_b128 v[212:215], v178 offset:6144
	ds_read_b128 v[216:219], v178 offset:7168
	s_waitcnt vmcnt(8)
	s_waitcnt lgkmcnt(0)
	s_barrier
	v_mfma_f32_16x16x32_bf16 v[124:127], v[128:131], v[188:191], v[124:127]
	v_mfma_f32_16x16x32_bf16 v[124:127], v[132:135], v[192:195], v[124:127]
	v_mfma_f32_16x16x32_bf16 v[120:123], v[140:143], v[192:195], v[120:123]
	v_mfma_f32_16x16x32_bf16 v[120:123], v[136:139], v[188:191], v[120:123]
	v_mfma_f32_16x16x32_bf16 v[116:119], v[144:147], v[188:191], v[116:119]
	v_mfma_f32_16x16x32_bf16 v[116:119], v[148:151], v[192:195], v[116:119]
	v_mfma_f32_16x16x32_bf16 v[112:115], v[184:187], v[192:195], v[112:115]
	v_mfma_f32_16x16x32_bf16 v[112:115], v[180:183], v[188:191], v[112:115]
	v_mfma_f32_16x16x32_bf16 v[96:99], v[180:183], v[196:199], v[96:99]
	v_mfma_f32_16x16x32_bf16 v[96:99], v[184:187], v[200:203], v[96:99]
	v_mfma_f32_16x16x32_bf16 v[100:103], v[148:151], v[200:203], v[100:103]
	v_mfma_f32_16x16x32_bf16 v[100:103], v[144:147], v[196:199], v[100:103]
	v_mfma_f32_16x16x32_bf16 v[104:107], v[136:139], v[196:199], v[104:107]
	v_mfma_f32_16x16x32_bf16 v[104:107], v[140:143], v[200:203], v[104:107]
	v_mfma_f32_16x16x32_bf16 v[108:111], v[132:135], v[200:203], v[108:111]
	v_mfma_f32_16x16x32_bf16 v[108:111], v[128:131], v[196:199], v[108:111]
	v_mfma_f32_16x16x32_bf16 v[92:95], v[128:131], v[204:207], v[92:95]
	v_mfma_f32_16x16x32_bf16 v[92:95], v[132:135], v[208:211], v[92:95]
	v_mfma_f32_16x16x32_bf16 v[88:91], v[140:143], v[208:211], v[88:91]
	v_mfma_f32_16x16x32_bf16 v[88:91], v[136:139], v[204:207], v[88:91]
	v_mfma_f32_16x16x32_bf16 v[84:87], v[144:147], v[204:207], v[84:87]
	v_mfma_f32_16x16x32_bf16 v[84:87], v[148:151], v[208:211], v[84:87]
	v_mfma_f32_16x16x32_bf16 v[80:83], v[184:187], v[208:211], v[80:83]
	v_mfma_f32_16x16x32_bf16 v[80:83], v[180:183], v[204:207], v[80:83]
	v_mfma_f32_16x16x32_bf16 v[64:67], v[180:183], v[212:215], v[64:67]
	v_mfma_f32_16x16x32_bf16 v[64:67], v[184:187], v[216:219], v[64:67]
	v_mfma_f32_16x16x32_bf16 v[68:71], v[148:151], v[216:219], v[68:71]
	v_mfma_f32_16x16x32_bf16 v[68:71], v[144:147], v[212:215], v[68:71]
	v_mfma_f32_16x16x32_bf16 v[72:75], v[136:139], v[212:215], v[72:75]
	v_mfma_f32_16x16x32_bf16 v[72:75], v[140:143], v[216:219], v[72:75]
	v_mfma_f32_16x16x32_bf16 v[76:79], v[132:135], v[216:219], v[76:79]
	v_mfma_f32_16x16x32_bf16 v[76:79], v[128:131], v[212:215], v[76:79]
	s_barrier
	s_add_i32 s41, s68, s33
	v_lshl_add_u64 v[172:173], s[30:31], 0, v[154:155]
	s_mov_b32 m0, s41
	v_lshl_add_u64 v[220:221], s[30:31], 0, v[158:159]
	global_load_lds_dwordx4 v[172:173], off
	s_add_i32 m0, s41, 0x2000
	s_add_u32 s42, s30, 0x100000
	s_addc_u32 s43, s31, 0
	s_add_i32 s41, s69, s33
	global_load_lds_dwordx4 v[220:221], off
	v_lshl_add_u64 v[188:189], s[42:43], 0, v[154:155]
	s_mov_b32 m0, s41
	v_lshl_add_u64 v[222:223], s[34:35], 0, v[152:153]
	global_load_lds_dwordx4 v[188:189], off
	v_lshl_add_u64 v[188:189], s[42:43], 0, v[158:159]
	s_add_i32 m0, s41, 0x2000
	v_lshl_add_u64 v[224:225], s[34:35], 0, v[156:157]
	global_load_lds_dwordx4 v[188:189], off
	s_mov_b32 m0, s7
	s_nop 0
	global_load_lds_dwordx4 v[222:223], off
	s_mov_b32 m0, s59
	s_nop 0
	global_load_lds_dwordx4 v[224:225], off
	ds_read_b128 v[188:191], v178 offset:16384
	ds_read_b128 v[192:195], v178 offset:17408
	ds_read_b128 v[196:199], v178 offset:18432
	ds_read_b128 v[200:203], v178 offset:19456
	ds_read_b128 v[204:207], v178 offset:20480
	ds_read_b128 v[208:211], v178 offset:21504
	ds_read_b128 v[212:215], v178 offset:22528
	ds_read_b128 v[216:219], v178 offset:23552
	s_waitcnt vmcnt(8)
	s_waitcnt lgkmcnt(0)
	s_barrier
	v_mfma_f32_16x16x32_bf16 v[60:63], v[128:131], v[188:191], v[60:63]
	v_mfma_f32_16x16x32_bf16 v[60:63], v[132:135], v[192:195], v[60:63]
	v_mfma_f32_16x16x32_bf16 v[56:59], v[140:143], v[192:195], v[56:59]
	v_mfma_f32_16x16x32_bf16 v[56:59], v[136:139], v[188:191], v[56:59]
	v_mfma_f32_16x16x32_bf16 v[52:55], v[144:147], v[188:191], v[52:55]
	v_mfma_f32_16x16x32_bf16 v[52:55], v[148:151], v[192:195], v[52:55]
	v_mfma_f32_16x16x32_bf16 v[48:51], v[184:187], v[192:195], v[48:51]
	v_mfma_f32_16x16x32_bf16 v[48:51], v[180:183], v[188:191], v[48:51]
	v_mfma_f32_16x16x32_bf16 v[32:35], v[180:183], v[196:199], v[32:35]
	v_mfma_f32_16x16x32_bf16 v[32:35], v[184:187], v[200:203], v[32:35]
	v_mfma_f32_16x16x32_bf16 v[36:39], v[148:151], v[200:203], v[36:39]
	v_mfma_f32_16x16x32_bf16 v[36:39], v[144:147], v[196:199], v[36:39]
	v_mfma_f32_16x16x32_bf16 v[40:43], v[136:139], v[196:199], v[40:43]
	v_mfma_f32_16x16x32_bf16 v[40:43], v[140:143], v[200:203], v[40:43]
	v_mfma_f32_16x16x32_bf16 v[44:47], v[132:135], v[200:203], v[44:47]
	v_mfma_f32_16x16x32_bf16 v[44:47], v[128:131], v[196:199], v[44:47]
	v_mfma_f32_16x16x32_bf16 v[28:31], v[128:131], v[204:207], v[28:31]
	v_mfma_f32_16x16x32_bf16 v[28:31], v[132:135], v[208:211], v[28:31]
	v_mfma_f32_16x16x32_bf16 v[24:27], v[140:143], v[208:211], v[24:27]
	v_mfma_f32_16x16x32_bf16 v[24:27], v[136:139], v[204:207], v[24:27]
	v_mfma_f32_16x16x32_bf16 v[20:23], v[144:147], v[204:207], v[20:23]
	v_mfma_f32_16x16x32_bf16 v[20:23], v[148:151], v[208:211], v[20:23]
	v_mfma_f32_16x16x32_bf16 v[16:19], v[184:187], v[208:211], v[16:19]
	v_mfma_f32_16x16x32_bf16 v[16:19], v[180:183], v[204:207], v[16:19]
	v_mfma_f32_16x16x32_bf16 v[0:3], v[180:183], v[212:215], v[0:3]
	v_mfma_f32_16x16x32_bf16 v[0:3], v[184:187], v[216:219], v[0:3]
	v_mfma_f32_16x16x32_bf16 v[4:7], v[148:151], v[216:219], v[4:7]
	v_mfma_f32_16x16x32_bf16 v[4:7], v[144:147], v[212:215], v[4:7]
	v_mfma_f32_16x16x32_bf16 v[8:11], v[136:139], v[212:215], v[8:11]
	v_mfma_f32_16x16x32_bf16 v[8:11], v[140:143], v[216:219], v[8:11]
	v_mfma_f32_16x16x32_bf16 v[12:15], v[132:135], v[216:219], v[12:15]
	v_mfma_f32_16x16x32_bf16 v[12:15], v[128:131], v[212:215], v[12:15]
	s_barrier
	s_add_i32 s41, 0, 0x18000
	s_add_i32 s42, 0, 0x1c000
	v_add_u32_e32 v140, s41, v174
	v_add_u32_e32 v184, s42, v174
	ds_read_b128 v[128:131], v140
	ds_read_b128 v[132:135], v140 offset:1024
	ds_read_b128 v[136:139], v140 offset:2048
	ds_read_b128 v[140:143], v140 offset:3072
	ds_read_b128 v[144:147], v184
	ds_read_b128 v[148:151], v184 offset:1024
	ds_read_b128 v[180:183], v184 offset:2048
	ds_read_b128 v[184:187], v184 offset:3072
	s_add_u32 s34, s34, 0x100000
	s_addc_u32 s35, s35, 0
	s_mov_b32 m0, s60
	v_lshl_add_u64 v[188:189], s[34:35], 0, v[152:153]
	global_load_lds_dwordx4 v[188:189], off
	v_lshl_add_u64 v[188:189], s[34:35], 0, v[156:157]
	s_mov_b32 m0, s61
	s_nop 0
	global_load_lds_dwordx4 v[188:189], off
	ds_read_b128 v[188:191], v178 offset:32768
	ds_read_b128 v[192:195], v178 offset:33792
	ds_read_b128 v[196:199], v178 offset:34816
	ds_read_b128 v[200:203], v178 offset:35840
	ds_read_b128 v[204:207], v178 offset:36864
	ds_read_b128 v[208:211], v178 offset:37888
	ds_read_b128 v[212:215], v178 offset:38912
	ds_read_b128 v[216:219], v178 offset:39936
	s_waitcnt vmcnt(8)
	s_waitcnt lgkmcnt(0)
	s_barrier
	v_mfma_f32_16x16x32_bf16 v[124:127], v[128:131], v[188:191], v[124:127]
	v_mfma_f32_16x16x32_bf16 v[124:127], v[132:135], v[192:195], v[124:127]
	v_mfma_f32_16x16x32_bf16 v[120:123], v[140:143], v[192:195], v[120:123]
	v_mfma_f32_16x16x32_bf16 v[120:123], v[136:139], v[188:191], v[120:123]
	v_mfma_f32_16x16x32_bf16 v[116:119], v[144:147], v[188:191], v[116:119]
	v_mfma_f32_16x16x32_bf16 v[116:119], v[148:151], v[192:195], v[116:119]
	v_mfma_f32_16x16x32_bf16 v[112:115], v[184:187], v[192:195], v[112:115]
	v_mfma_f32_16x16x32_bf16 v[112:115], v[180:183], v[188:191], v[112:115]
	v_mfma_f32_16x16x32_bf16 v[96:99], v[180:183], v[196:199], v[96:99]
	v_mfma_f32_16x16x32_bf16 v[96:99], v[184:187], v[200:203], v[96:99]
	v_mfma_f32_16x16x32_bf16 v[100:103], v[148:151], v[200:203], v[100:103]
	v_mfma_f32_16x16x32_bf16 v[100:103], v[144:147], v[196:199], v[100:103]
	v_mfma_f32_16x16x32_bf16 v[104:107], v[136:139], v[196:199], v[104:107]
	v_mfma_f32_16x16x32_bf16 v[104:107], v[140:143], v[200:203], v[104:107]
	v_mfma_f32_16x16x32_bf16 v[108:111], v[132:135], v[200:203], v[108:111]
	v_mfma_f32_16x16x32_bf16 v[108:111], v[128:131], v[196:199], v[108:111]
	v_mfma_f32_16x16x32_bf16 v[92:95], v[128:131], v[204:207], v[92:95]
	v_mfma_f32_16x16x32_bf16 v[92:95], v[132:135], v[208:211], v[92:95]
	v_mfma_f32_16x16x32_bf16 v[88:91], v[140:143], v[208:211], v[88:91]
	v_mfma_f32_16x16x32_bf16 v[88:91], v[136:139], v[204:207], v[88:91]
	v_mfma_f32_16x16x32_bf16 v[84:87], v[144:147], v[204:207], v[84:87]
	v_mfma_f32_16x16x32_bf16 v[84:87], v[148:151], v[208:211], v[84:87]
	v_mfma_f32_16x16x32_bf16 v[80:83], v[184:187], v[208:211], v[80:83]
	v_mfma_f32_16x16x32_bf16 v[80:83], v[180:183], v[204:207], v[80:83]
	v_mfma_f32_16x16x32_bf16 v[64:67], v[180:183], v[212:215], v[64:67]
	v_mfma_f32_16x16x32_bf16 v[64:67], v[184:187], v[216:219], v[64:67]
	v_mfma_f32_16x16x32_bf16 v[68:71], v[148:151], v[216:219], v[68:71]
	v_mfma_f32_16x16x32_bf16 v[68:71], v[144:147], v[212:215], v[68:71]
	v_mfma_f32_16x16x32_bf16 v[72:75], v[136:139], v[212:215], v[72:75]
	v_mfma_f32_16x16x32_bf16 v[72:75], v[140:143], v[216:219], v[72:75]
	v_mfma_f32_16x16x32_bf16 v[76:79], v[132:135], v[216:219], v[76:79]
	v_mfma_f32_16x16x32_bf16 v[76:79], v[128:131], v[212:215], v[76:79]
	s_barrier
	s_add_i32 s34, s41, s33
	v_lshl_add_u64 v[172:173], v[172:173], 0, s[16:17]
	s_mov_b32 m0, s34
	s_nop 0
	global_load_lds_dwordx4 v[172:173], off
	s_add_i32 m0, s34, 0x2000
	s_add_u32 s30, s30, 0x100800
	v_lshl_add_u64 v[172:173], v[220:221], 0, s[16:17]
	s_addc_u32 s31, s31, 0
	s_add_i32 s34, s42, s33
	global_load_lds_dwordx4 v[172:173], off
	v_lshl_add_u64 v[172:173], s[30:31], 0, v[154:155]
	s_mov_b32 m0, s34
	s_nop 0
	global_load_lds_dwordx4 v[172:173], off
	v_lshl_add_u64 v[172:173], s[30:31], 0, v[158:159]
	s_add_i32 m0, s34, 0x2000
	s_nop 0
	global_load_lds_dwordx4 v[172:173], off
	v_lshl_add_u64 v[172:173], v[222:223], 0, s[18:19]
	s_mov_b32 m0, s63
	s_nop 0
	global_load_lds_dwordx4 v[172:173], off
	v_lshl_add_u64 v[172:173], v[224:225], 0, s[18:19]
	s_mov_b32 m0, s64
	s_nop 0
	global_load_lds_dwordx4 v[172:173], off
	ds_read_b128 v[188:191], v178 offset:49152
	ds_read_b128 v[192:195], v178 offset:50176
	ds_read_b128 v[196:199], v178 offset:51200
	ds_read_b128 v[200:203], v178 offset:52224
	ds_read_b128 v[204:207], v178 offset:53248
	ds_read_b128 v[208:211], v178 offset:54272
	ds_read_b128 v[212:215], v178 offset:55296
	ds_read_b128 v[216:219], v178 offset:56320
	s_waitcnt vmcnt(8)
	s_waitcnt lgkmcnt(0)
	s_barrier
	v_mfma_f32_16x16x32_bf16 v[60:63], v[128:131], v[188:191], v[60:63]
	v_mfma_f32_16x16x32_bf16 v[60:63], v[132:135], v[192:195], v[60:63]
	v_mfma_f32_16x16x32_bf16 v[56:59], v[140:143], v[192:195], v[56:59]
	v_mfma_f32_16x16x32_bf16 v[56:59], v[136:139], v[188:191], v[56:59]
	v_mfma_f32_16x16x32_bf16 v[52:55], v[144:147], v[188:191], v[52:55]
	v_mfma_f32_16x16x32_bf16 v[52:55], v[148:151], v[192:195], v[52:55]
	v_mfma_f32_16x16x32_bf16 v[48:51], v[184:187], v[192:195], v[48:51]
	v_mfma_f32_16x16x32_bf16 v[48:51], v[180:183], v[188:191], v[48:51]
	v_mfma_f32_16x16x32_bf16 v[32:35], v[180:183], v[196:199], v[32:35]
	v_mfma_f32_16x16x32_bf16 v[32:35], v[184:187], v[200:203], v[32:35]
	v_mfma_f32_16x16x32_bf16 v[36:39], v[148:151], v[200:203], v[36:39]
	v_mfma_f32_16x16x32_bf16 v[36:39], v[144:147], v[196:199], v[36:39]
	v_mfma_f32_16x16x32_bf16 v[40:43], v[136:139], v[196:199], v[40:43]
	v_mfma_f32_16x16x32_bf16 v[40:43], v[140:143], v[200:203], v[40:43]
	v_mfma_f32_16x16x32_bf16 v[44:47], v[132:135], v[200:203], v[44:47]
	v_mfma_f32_16x16x32_bf16 v[44:47], v[128:131], v[196:199], v[44:47]
	v_mfma_f32_16x16x32_bf16 v[28:31], v[128:131], v[204:207], v[28:31]
	v_mfma_f32_16x16x32_bf16 v[28:31], v[132:135], v[208:211], v[28:31]
	v_mfma_f32_16x16x32_bf16 v[24:27], v[140:143], v[208:211], v[24:27]
	v_mfma_f32_16x16x32_bf16 v[24:27], v[136:139], v[204:207], v[24:27]
	v_mfma_f32_16x16x32_bf16 v[20:23], v[144:147], v[204:207], v[20:23]
	v_mfma_f32_16x16x32_bf16 v[20:23], v[148:151], v[208:211], v[20:23]
	v_mfma_f32_16x16x32_bf16 v[16:19], v[184:187], v[208:211], v[16:19]
	v_mfma_f32_16x16x32_bf16 v[16:19], v[180:183], v[204:207], v[16:19]
	v_mfma_f32_16x16x32_bf16 v[0:3], v[180:183], v[212:215], v[0:3]
	v_mfma_f32_16x16x32_bf16 v[0:3], v[184:187], v[216:219], v[0:3]
	v_mfma_f32_16x16x32_bf16 v[4:7], v[148:151], v[216:219], v[4:7]
	v_mfma_f32_16x16x32_bf16 v[4:7], v[144:147], v[212:215], v[4:7]
	v_mfma_f32_16x16x32_bf16 v[8:11], v[136:139], v[212:215], v[8:11]
	v_mfma_f32_16x16x32_bf16 v[8:11], v[140:143], v[216:219], v[8:11]
	v_mfma_f32_16x16x32_bf16 v[12:15], v[132:135], v[216:219], v[12:15]
	v_mfma_f32_16x16x32_bf16 v[12:15], v[128:131], v[212:215], v[12:15]
	s_barrier
	s_add_i32 s40, s40, 2
	s_add_u32 s38, s38, 0x1000
	s_addc_u32 s39, s39, 0
	s_add_u32 s28, s28, 0x100
	s_addc_u32 s29, s29, 0
	s_cmp_gt_u32 s40, 61
	s_cbranch_scc0 .LBB0_1202

.LBB0_1263:
	ds_read_b128 v[146:149], v152
	ds_read_b128 v[156:159], v152 offset:1024
	ds_read_b128 v[160:163], v152 offset:2048
	ds_read_b128 v[164:167], v152 offset:3072
	ds_read_b128 v[168:171], v153
	ds_read_b128 v[172:175], v153 offset:1024
	ds_read_b128 v[176:179], v153 offset:2048
	ds_read_b128 v[180:183], v153 offset:3072
	s_add_u32 s22, s20, 0x100
	s_addc_u32 s23, s21, 0
	s_cmp_eq_u32 s46, 12
	s_cselect_b32 s27, s5, s23
	s_cselect_b32 s26, s4, s22
	s_cselect_b32 s25, s19, s15
	s_cselect_b32 s24, s18, s6
	v_lshl_add_u64 v[184:185], s[20:21], 0, v[136:137]
	s_add_i32 m0, s17, 0xc000
	s_nop 0
	global_load_lds_dwordx4 v[184:185], off
	v_lshl_add_u64 v[184:185], s[20:21], 0, v[138:139]
	s_add_i32 m0, s17, 0xe000
	s_nop 0
	global_load_lds_dwordx4 v[184:185], off
	ds_read_b128 v[184:187], v154
	ds_read_b128 v[188:191], v154 offset:1024
	ds_read_b128 v[192:195], v154 offset:2048
	ds_read_b128 v[196:199], v154 offset:3072
	ds_read_b128 v[200:203], v154 offset:4096
	ds_read_b128 v[204:207], v154 offset:5120
	ds_read_b128 v[208:211], v154 offset:6144
	ds_read_b128 v[212:215], v154 offset:7168
	s_waitcnt vmcnt(8)
	s_waitcnt lgkmcnt(0)
	s_barrier
	v_mfma_f32_16x16x32_bf16 v[124:127], v[146:149], v[184:187], v[124:127]
	v_mfma_f32_16x16x32_bf16 v[124:127], v[156:159], v[188:191], v[124:127]
	v_mfma_f32_16x16x32_bf16 v[120:123], v[164:167], v[188:191], v[120:123]
	v_mfma_f32_16x16x32_bf16 v[120:123], v[160:163], v[184:187], v[120:123]
	v_mfma_f32_16x16x32_bf16 v[116:119], v[168:171], v[184:187], v[116:119]
	v_mfma_f32_16x16x32_bf16 v[116:119], v[172:175], v[188:191], v[116:119]
	v_mfma_f32_16x16x32_bf16 v[108:111], v[180:183], v[188:191], v[108:111]
	v_mfma_f32_16x16x32_bf16 v[108:111], v[176:179], v[184:187], v[108:111]
	v_mfma_f32_16x16x32_bf16 v[92:95], v[176:179], v[192:195], v[92:95]
	v_mfma_f32_16x16x32_bf16 v[92:95], v[180:183], v[196:199], v[92:95]
	v_mfma_f32_16x16x32_bf16 v[100:103], v[172:175], v[196:199], v[100:103]
	v_mfma_f32_16x16x32_bf16 v[100:103], v[168:171], v[192:195], v[100:103]
	v_mfma_f32_16x16x32_bf16 v[104:107], v[160:163], v[192:195], v[104:107]
	v_mfma_f32_16x16x32_bf16 v[104:107], v[164:167], v[196:199], v[104:107]
	v_mfma_f32_16x16x32_bf16 v[112:115], v[156:159], v[196:199], v[112:115]
	v_mfma_f32_16x16x32_bf16 v[112:115], v[146:149], v[192:195], v[112:115]
	v_mfma_f32_16x16x32_bf16 v[96:99], v[146:149], v[200:203], v[96:99]
	v_mfma_f32_16x16x32_bf16 v[96:99], v[156:159], v[204:207], v[96:99]
	v_mfma_f32_16x16x32_bf16 v[88:91], v[164:167], v[204:207], v[88:91]
	v_mfma_f32_16x16x32_bf16 v[88:91], v[160:163], v[200:203], v[88:91]
	v_mfma_f32_16x16x32_bf16 v[84:87], v[168:171], v[200:203], v[84:87]
	v_mfma_f32_16x16x32_bf16 v[84:87], v[172:175], v[204:207], v[84:87]
	v_mfma_f32_16x16x32_bf16 v[76:79], v[180:183], v[204:207], v[76:79]
	v_mfma_f32_16x16x32_bf16 v[76:79], v[176:179], v[200:203], v[76:79]
	v_mfma_f32_16x16x32_bf16 v[64:67], v[176:179], v[208:211], v[64:67]
	v_mfma_f32_16x16x32_bf16 v[64:67], v[180:183], v[212:215], v[64:67]
	v_mfma_f32_16x16x32_bf16 v[68:71], v[172:175], v[212:215], v[68:71]
	v_mfma_f32_16x16x32_bf16 v[68:71], v[168:171], v[208:211], v[68:71]
	v_mfma_f32_16x16x32_bf16 v[72:75], v[160:163], v[208:211], v[72:75]
	v_mfma_f32_16x16x32_bf16 v[72:75], v[164:167], v[212:215], v[72:75]
	v_mfma_f32_16x16x32_bf16 v[80:83], v[156:159], v[212:215], v[80:83]
	v_mfma_f32_16x16x32_bf16 v[80:83], v[146:149], v[208:211], v[80:83]
	s_barrier
	s_add_i32 s20, s41, s33
	v_lshl_add_u64 v[216:217], s[24:25], 0, v[130:131]
	s_mov_b32 m0, s20
	v_lshl_add_u64 v[218:219], s[24:25], 0, v[134:135]
	global_load_lds_dwordx4 v[216:217], off
	s_add_i32 m0, s20, 0x2000
	s_add_u32 s20, s24, 0x200000
	s_addc_u32 s21, s25, 0
	s_add_i32 s47, s42, s33
	global_load_lds_dwordx4 v[218:219], off
	v_lshl_add_u64 v[184:185], s[20:21], 0, v[130:131]
	s_mov_b32 m0, s47
	v_lshl_add_u64 v[220:221], s[26:27], 0, v[128:129]
	global_load_lds_dwordx4 v[184:185], off
	v_lshl_add_u64 v[184:185], s[20:21], 0, v[134:135]
	s_add_i32 m0, s47, 0x2000
	v_lshl_add_u64 v[222:223], s[26:27], 0, v[132:133]
	global_load_lds_dwordx4 v[184:185], off
	s_mov_b32 m0, s17
	s_nop 0
	global_load_lds_dwordx4 v[220:221], off
	s_mov_b32 m0, s34
	s_nop 0
	global_load_lds_dwordx4 v[222:223], off
	ds_read_b128 v[184:187], v154 offset:16384
	ds_read_b128 v[188:191], v154 offset:17408
	ds_read_b128 v[192:195], v154 offset:18432
	ds_read_b128 v[196:199], v154 offset:19456
	ds_read_b128 v[200:203], v154 offset:20480
	ds_read_b128 v[204:207], v154 offset:21504
	ds_read_b128 v[208:211], v154 offset:22528
	ds_read_b128 v[212:215], v154 offset:23552
	s_waitcnt vmcnt(8)
	s_waitcnt lgkmcnt(0)
	s_barrier
	v_mfma_f32_16x16x32_bf16 v[60:63], v[146:149], v[184:187], v[60:63]
	v_mfma_f32_16x16x32_bf16 v[60:63], v[156:159], v[188:191], v[60:63]
	v_mfma_f32_16x16x32_bf16 v[56:59], v[164:167], v[188:191], v[56:59]
	v_mfma_f32_16x16x32_bf16 v[56:59], v[160:163], v[184:187], v[56:59]
	v_mfma_f32_16x16x32_bf16 v[52:55], v[168:171], v[184:187], v[52:55]
	v_mfma_f32_16x16x32_bf16 v[52:55], v[172:175], v[188:191], v[52:55]
	v_mfma_f32_16x16x32_bf16 v[44:47], v[180:183], v[188:191], v[44:47]
	v_mfma_f32_16x16x32_bf16 v[44:47], v[176:179], v[184:187], v[44:47]
	v_mfma_f32_16x16x32_bf16 v[28:31], v[176:179], v[192:195], v[28:31]
	v_mfma_f32_16x16x32_bf16 v[28:31], v[180:183], v[196:199], v[28:31]
	v_mfma_f32_16x16x32_bf16 v[36:39], v[172:175], v[196:199], v[36:39]
	v_mfma_f32_16x16x32_bf16 v[36:39], v[168:171], v[192:195], v[36:39]
	v_mfma_f32_16x16x32_bf16 v[40:43], v[160:163], v[192:195], v[40:43]
	v_mfma_f32_16x16x32_bf16 v[40:43], v[164:167], v[196:199], v[40:43]
	v_mfma_f32_16x16x32_bf16 v[48:51], v[156:159], v[196:199], v[48:51]
	v_mfma_f32_16x16x32_bf16 v[48:51], v[146:149], v[192:195], v[48:51]
	v_mfma_f32_16x16x32_bf16 v[32:35], v[146:149], v[200:203], v[32:35]
	v_mfma_f32_16x16x32_bf16 v[32:35], v[156:159], v[204:207], v[32:35]
	v_mfma_f32_16x16x32_bf16 v[24:27], v[164:167], v[204:207], v[24:27]
	v_mfma_f32_16x16x32_bf16 v[24:27], v[160:163], v[200:203], v[24:27]
	v_mfma_f32_16x16x32_bf16 v[20:23], v[168:171], v[200:203], v[20:23]
	v_mfma_f32_16x16x32_bf16 v[20:23], v[172:175], v[204:207], v[20:23]
	v_mfma_f32_16x16x32_bf16 v[12:15], v[180:183], v[204:207], v[12:15]
	v_mfma_f32_16x16x32_bf16 v[12:15], v[176:179], v[200:203], v[12:15]
	v_mfma_f32_16x16x32_bf16 v[0:3], v[176:179], v[208:211], v[0:3]
	v_mfma_f32_16x16x32_bf16 v[0:3], v[180:183], v[212:215], v[0:3]
	v_mfma_f32_16x16x32_bf16 v[4:7], v[172:175], v[212:215], v[4:7]
	v_mfma_f32_16x16x32_bf16 v[4:7], v[168:171], v[208:211], v[4:7]
	v_mfma_f32_16x16x32_bf16 v[8:11], v[160:163], v[208:211], v[8:11]
	v_mfma_f32_16x16x32_bf16 v[8:11], v[164:167], v[212:215], v[8:11]
	v_mfma_f32_16x16x32_bf16 v[16:19], v[156:159], v[212:215], v[16:19]
	v_mfma_f32_16x16x32_bf16 v[16:19], v[146:149], v[208:211], v[16:19]
	s_barrier
	s_add_i32 s47, 0, 0x18000
	v_add_u32_e32 v144, s47, v145
	s_add_i32 s48, 0, 0x1c000
	ds_read_b128 v[146:149], v144
	ds_read_b128 v[156:159], v144 offset:1024
	ds_read_b128 v[160:163], v144 offset:2048
	ds_read_b128 v[164:167], v144 offset:3072
	v_add_u32_e32 v144, s48, v145
	ds_read_b128 v[168:171], v144
	ds_read_b128 v[172:175], v144 offset:1024
	ds_read_b128 v[176:179], v144 offset:2048
	ds_read_b128 v[180:183], v144 offset:3072
	s_add_u32 s20, s26, 0x200000
	s_addc_u32 s21, s27, 0
	s_mov_b32 m0, s35
	v_lshl_add_u64 v[184:185], s[20:21], 0, v[128:129]
	global_load_lds_dwordx4 v[184:185], off
	v_lshl_add_u64 v[184:185], s[20:21], 0, v[132:133]
	s_mov_b32 m0, s36
	s_nop 0
	global_load_lds_dwordx4 v[184:185], off
	ds_read_b128 v[184:187], v154 offset:32768
	ds_read_b128 v[188:191], v154 offset:33792
	ds_read_b128 v[192:195], v154 offset:34816
	ds_read_b128 v[196:199], v154 offset:35840
	ds_read_b128 v[200:203], v154 offset:36864
	ds_read_b128 v[204:207], v154 offset:37888
	ds_read_b128 v[208:211], v154 offset:38912
	ds_read_b128 v[212:215], v154 offset:39936
	s_waitcnt vmcnt(8)
	s_waitcnt lgkmcnt(0)
	s_barrier
	v_mfma_f32_16x16x32_bf16 v[124:127], v[146:149], v[184:187], v[124:127]
	v_mfma_f32_16x16x32_bf16 v[124:127], v[156:159], v[188:191], v[124:127]
	v_mfma_f32_16x16x32_bf16 v[120:123], v[164:167], v[188:191], v[120:123]
	v_mfma_f32_16x16x32_bf16 v[120:123], v[160:163], v[184:187], v[120:123]
	v_mfma_f32_16x16x32_bf16 v[116:119], v[168:171], v[184:187], v[116:119]
	v_mfma_f32_16x16x32_bf16 v[116:119], v[172:175], v[188:191], v[116:119]
	v_mfma_f32_16x16x32_bf16 v[108:111], v[180:183], v[188:191], v[108:111]
	v_mfma_f32_16x16x32_bf16 v[108:111], v[176:179], v[184:187], v[108:111]
	v_mfma_f32_16x16x32_bf16 v[92:95], v[176:179], v[192:195], v[92:95]
	v_mfma_f32_16x16x32_bf16 v[92:95], v[180:183], v[196:199], v[92:95]
	v_mfma_f32_16x16x32_bf16 v[100:103], v[172:175], v[196:199], v[100:103]
	v_mfma_f32_16x16x32_bf16 v[100:103], v[168:171], v[192:195], v[100:103]
	v_mfma_f32_16x16x32_bf16 v[104:107], v[160:163], v[192:195], v[104:107]
	v_mfma_f32_16x16x32_bf16 v[104:107], v[164:167], v[196:199], v[104:107]
	v_mfma_f32_16x16x32_bf16 v[112:115], v[156:159], v[196:199], v[112:115]
	v_mfma_f32_16x16x32_bf16 v[112:115], v[146:149], v[192:195], v[112:115]
	v_mfma_f32_16x16x32_bf16 v[96:99], v[146:149], v[200:203], v[96:99]
	v_mfma_f32_16x16x32_bf16 v[96:99], v[156:159], v[204:207], v[96:99]
	v_mfma_f32_16x16x32_bf16 v[88:91], v[164:167], v[204:207], v[88:91]
	v_mfma_f32_16x16x32_bf16 v[88:91], v[160:163], v[200:203], v[88:91]
	v_mfma_f32_16x16x32_bf16 v[84:87], v[168:171], v[200:203], v[84:87]
	v_mfma_f32_16x16x32_bf16 v[84:87], v[172:175], v[204:207], v[84:87]
	v_mfma_f32_16x16x32_bf16 v[76:79], v[180:183], v[204:207], v[76:79]
	v_mfma_f32_16x16x32_bf16 v[76:79], v[176:179], v[200:203], v[76:79]
	v_mfma_f32_16x16x32_bf16 v[64:67], v[176:179], v[208:211], v[64:67]
	v_mfma_f32_16x16x32_bf16 v[64:67], v[180:183], v[212:215], v[64:67]
	v_mfma_f32_16x16x32_bf16 v[68:71], v[172:175], v[212:215], v[68:71]
	v_mfma_f32_16x16x32_bf16 v[68:71], v[168:171], v[208:211], v[68:71]
	v_mfma_f32_16x16x32_bf16 v[72:75], v[160:163], v[208:211], v[72:75]
	v_mfma_f32_16x16x32_bf16 v[72:75], v[164:167], v[212:215], v[72:75]
	v_mfma_f32_16x16x32_bf16 v[80:83], v[156:159], v[212:215], v[80:83]
	v_mfma_f32_16x16x32_bf16 v[80:83], v[146:149], v[208:211], v[80:83]
	s_barrier
	s_add_i32 s20, s47, s33
	v_lshl_add_u64 v[184:185], v[216:217], 0, s[12:13]
	s_mov_b32 m0, s20
	s_nop 0
	global_load_lds_dwordx4 v[184:185], off
	s_add_i32 m0, s20, 0x2000
	s_add_u32 s20, s24, 0x200080
	v_lshl_add_u64 v[184:185], v[218:219], 0, s[12:13]
	s_addc_u32 s21, s25, 0
	s_add_i32 s24, s48, s33
	global_load_lds_dwordx4 v[184:185], off
	v_lshl_add_u64 v[184:185], s[20:21], 0, v[130:131]
	s_mov_b32 m0, s24
	s_nop 0
	global_load_lds_dwordx4 v[184:185], off
	v_lshl_add_u64 v[184:185], s[20:21], 0, v[134:135]
	s_add_i32 m0, s24, 0x2000
	s_nop 0
	global_load_lds_dwordx4 v[184:185], off
	v_lshl_add_u64 v[184:185], v[220:221], 0, s[12:13]
	s_mov_b32 m0, s37
	s_nop 0
	global_load_lds_dwordx4 v[184:185], off
	v_lshl_add_u64 v[184:185], v[222:223], 0, s[12:13]
	s_mov_b32 m0, s38
	s_nop 0
	global_load_lds_dwordx4 v[184:185], off
	ds_read_b128 v[184:187], v154 offset:49152
	ds_read_b128 v[188:191], v154 offset:50176
	ds_read_b128 v[192:195], v154 offset:51200
	ds_read_b128 v[196:199], v154 offset:52224
	ds_read_b128 v[200:203], v154 offset:53248
	ds_read_b128 v[204:207], v154 offset:54272
	ds_read_b128 v[208:211], v154 offset:55296
	ds_read_b128 v[212:215], v154 offset:56320
	s_waitcnt vmcnt(8)
	s_waitcnt lgkmcnt(0)
	s_barrier
	v_mfma_f32_16x16x32_bf16 v[60:63], v[146:149], v[184:187], v[60:63]
	v_mfma_f32_16x16x32_bf16 v[60:63], v[156:159], v[188:191], v[60:63]
	v_mfma_f32_16x16x32_bf16 v[56:59], v[164:167], v[188:191], v[56:59]
	v_mfma_f32_16x16x32_bf16 v[56:59], v[160:163], v[184:187], v[56:59]
	v_mfma_f32_16x16x32_bf16 v[52:55], v[168:171], v[184:187], v[52:55]
	v_mfma_f32_16x16x32_bf16 v[52:55], v[172:175], v[188:191], v[52:55]
	v_mfma_f32_16x16x32_bf16 v[44:47], v[180:183], v[188:191], v[44:47]
	v_mfma_f32_16x16x32_bf16 v[44:47], v[176:179], v[184:187], v[44:47]
	v_mfma_f32_16x16x32_bf16 v[28:31], v[176:179], v[192:195], v[28:31]
	v_mfma_f32_16x16x32_bf16 v[28:31], v[180:183], v[196:199], v[28:31]
	v_mfma_f32_16x16x32_bf16 v[36:39], v[172:175], v[196:199], v[36:39]
	v_mfma_f32_16x16x32_bf16 v[36:39], v[168:171], v[192:195], v[36:39]
	v_mfma_f32_16x16x32_bf16 v[40:43], v[160:163], v[192:195], v[40:43]
	v_mfma_f32_16x16x32_bf16 v[40:43], v[164:167], v[196:199], v[40:43]
	v_mfma_f32_16x16x32_bf16 v[48:51], v[156:159], v[196:199], v[48:51]
	v_mfma_f32_16x16x32_bf16 v[48:51], v[146:149], v[192:195], v[48:51]
	v_mfma_f32_16x16x32_bf16 v[32:35], v[146:149], v[200:203], v[32:35]
	v_mfma_f32_16x16x32_bf16 v[32:35], v[156:159], v[204:207], v[32:35]
	v_mfma_f32_16x16x32_bf16 v[24:27], v[164:167], v[204:207], v[24:27]
	v_mfma_f32_16x16x32_bf16 v[24:27], v[160:163], v[200:203], v[24:27]
	v_mfma_f32_16x16x32_bf16 v[20:23], v[168:171], v[200:203], v[20:23]
	v_mfma_f32_16x16x32_bf16 v[20:23], v[172:175], v[204:207], v[20:23]
	v_mfma_f32_16x16x32_bf16 v[12:15], v[180:183], v[204:207], v[12:15]
	v_mfma_f32_16x16x32_bf16 v[12:15], v[176:179], v[200:203], v[12:15]
	v_mfma_f32_16x16x32_bf16 v[0:3], v[176:179], v[208:211], v[0:3]
	v_mfma_f32_16x16x32_bf16 v[0:3], v[180:183], v[212:215], v[0:3]
	v_mfma_f32_16x16x32_bf16 v[4:7], v[172:175], v[212:215], v[4:7]
	v_mfma_f32_16x16x32_bf16 v[4:7], v[168:171], v[208:211], v[4:7]
	v_mfma_f32_16x16x32_bf16 v[8:11], v[160:163], v[208:211], v[8:11]
	v_mfma_f32_16x16x32_bf16 v[8:11], v[164:167], v[212:215], v[8:11]
	v_mfma_f32_16x16x32_bf16 v[16:19], v[156:159], v[212:215], v[16:19]
	v_mfma_f32_16x16x32_bf16 v[16:19], v[146:149], v[208:211], v[16:19]
	s_barrier
	s_add_i32 s46, s46, 2
	s_add_u32 s6, s6, 0x100
	s_addc_u32 s15, s15, 0
	s_cmp_gt_u32 s46, 13
	s_mov_b64 s[20:21], s[22:23]
	s_cbranch_scc0 .LBB0_1263
	s_and_b64 vcc, exec, s[8:9]
	s_cbranch_vccz .LBB0_1266
	s_barrier

.LBB0_1340:
	v_add_u32_e32 v166, s51, v152
	v_add_u32_e32 v182, s52, v152
	ds_read_b128 v[154:157], v166
	ds_read_b128 v[158:161], v166 offset:1024
	ds_read_b128 v[162:165], v166 offset:2048
	ds_read_b128 v[166:169], v166 offset:3072
	ds_read_b128 v[170:173], v182
	ds_read_b128 v[174:177], v182 offset:1024
	ds_read_b128 v[178:181], v182 offset:2048
	ds_read_b128 v[182:185], v182 offset:3072
	s_add_u32 s30, s10, s28
	s_addc_u32 s31, s11, s29
	s_cmp_eq_u32 s58, 60
	s_cselect_b32 s35, s23, s31
	s_cselect_b32 s34, s54, s30
	s_cselect_b32 s31, s21, s57
	s_cselect_b32 s30, s55, s56
	v_lshl_add_u64 v[186:187], s[10:11], 0, v[146:147]
	s_add_i32 m0, s44, 0xc000
	s_nop 0
	global_load_lds_dwordx4 v[186:187], off
	v_lshl_add_u64 v[186:187], s[10:11], 0, v[144:145]
	s_add_i32 m0, s44, 0xe000
	s_nop 0
	global_load_lds_dwordx4 v[186:187], off
	ds_read_b128 v[186:189], v153
	ds_read_b128 v[190:193], v153 offset:1024
	ds_read_b128 v[194:197], v153 offset:2048
	ds_read_b128 v[198:201], v153 offset:3072
	ds_read_b128 v[202:205], v153 offset:4096
	ds_read_b128 v[206:209], v153 offset:5120
	ds_read_b128 v[210:213], v153 offset:6144
	ds_read_b128 v[214:217], v153 offset:7168
	s_waitcnt vmcnt(8)
	s_waitcnt lgkmcnt(0)
	s_barrier
	v_mfma_f32_16x16x32_bf16 v[124:127], v[154:157], v[186:189], v[124:127]
	v_mfma_f32_16x16x32_bf16 v[124:127], v[158:161], v[190:193], v[124:127]
	v_mfma_f32_16x16x32_bf16 v[120:123], v[166:169], v[190:193], v[120:123]
	v_mfma_f32_16x16x32_bf16 v[120:123], v[162:165], v[186:189], v[120:123]
	v_mfma_f32_16x16x32_bf16 v[116:119], v[170:173], v[186:189], v[116:119]
	v_mfma_f32_16x16x32_bf16 v[116:119], v[174:177], v[190:193], v[116:119]
	v_mfma_f32_16x16x32_bf16 v[112:115], v[182:185], v[190:193], v[112:115]
	v_mfma_f32_16x16x32_bf16 v[112:115], v[178:181], v[186:189], v[112:115]
	v_mfma_f32_16x16x32_bf16 v[96:99], v[178:181], v[194:197], v[96:99]
	v_mfma_f32_16x16x32_bf16 v[96:99], v[182:185], v[198:201], v[96:99]
	v_mfma_f32_16x16x32_bf16 v[100:103], v[174:177], v[198:201], v[100:103]
	v_mfma_f32_16x16x32_bf16 v[100:103], v[170:173], v[194:197], v[100:103]
	v_mfma_f32_16x16x32_bf16 v[104:107], v[162:165], v[194:197], v[104:107]
	v_mfma_f32_16x16x32_bf16 v[104:107], v[166:169], v[198:201], v[104:107]
	v_mfma_f32_16x16x32_bf16 v[108:111], v[158:161], v[198:201], v[108:111]
	v_mfma_f32_16x16x32_bf16 v[108:111], v[154:157], v[194:197], v[108:111]
	v_mfma_f32_16x16x32_bf16 v[92:95], v[154:157], v[202:205], v[92:95]
	v_mfma_f32_16x16x32_bf16 v[92:95], v[158:161], v[206:209], v[92:95]
	v_mfma_f32_16x16x32_bf16 v[88:91], v[166:169], v[206:209], v[88:91]
	v_mfma_f32_16x16x32_bf16 v[88:91], v[162:165], v[202:205], v[88:91]
	v_mfma_f32_16x16x32_bf16 v[84:87], v[170:173], v[202:205], v[84:87]
	v_mfma_f32_16x16x32_bf16 v[84:87], v[174:177], v[206:209], v[84:87]
	v_mfma_f32_16x16x32_bf16 v[80:83], v[182:185], v[206:209], v[80:83]
	v_mfma_f32_16x16x32_bf16 v[80:83], v[178:181], v[202:205], v[80:83]
	v_mfma_f32_16x16x32_bf16 v[64:67], v[178:181], v[210:213], v[64:67]
	v_mfma_f32_16x16x32_bf16 v[64:67], v[182:185], v[214:217], v[64:67]
	v_mfma_f32_16x16x32_bf16 v[68:71], v[174:177], v[214:217], v[68:71]
	v_mfma_f32_16x16x32_bf16 v[68:71], v[170:173], v[210:213], v[68:71]
	v_mfma_f32_16x16x32_bf16 v[72:75], v[162:165], v[210:213], v[72:75]
	v_mfma_f32_16x16x32_bf16 v[72:75], v[166:169], v[214:217], v[72:75]
	v_mfma_f32_16x16x32_bf16 v[76:79], v[158:161], v[214:217], v[76:79]
	v_mfma_f32_16x16x32_bf16 v[76:79], v[154:157], v[210:213], v[76:79]
	s_barrier
	s_add_i32 s59, s51, s43
	v_lshl_add_u64 v[218:219], s[30:31], 0, v[130:131]
	s_mov_b32 m0, s59
	v_lshl_add_u64 v[220:221], s[30:31], 0, v[134:135]
	global_load_lds_dwordx4 v[218:219], off
	s_add_i32 m0, s59, 0x2000
	s_add_u32 s60, s30, 0x100000
	s_addc_u32 s61, s31, 0
	s_add_i32 s59, s52, s43
	global_load_lds_dwordx4 v[220:221], off
	v_lshl_add_u64 v[186:187], s[60:61], 0, v[130:131]
	s_mov_b32 m0, s59
	v_lshl_add_u64 v[222:223], s[34:35], 0, v[128:129]
	global_load_lds_dwordx4 v[186:187], off
	v_lshl_add_u64 v[186:187], s[60:61], 0, v[134:135]
	s_add_i32 m0, s59, 0x2000
	v_lshl_add_u64 v[224:225], s[34:35], 0, v[132:133]
	global_load_lds_dwordx4 v[186:187], off
	s_mov_b32 m0, s44
	s_nop 0
	global_load_lds_dwordx4 v[222:223], off
	s_mov_b32 m0, s45
	s_nop 0
	global_load_lds_dwordx4 v[224:225], off
	ds_read_b128 v[186:189], v153 offset:16384
	ds_read_b128 v[190:193], v153 offset:17408
	ds_read_b128 v[194:197], v153 offset:18432
	ds_read_b128 v[198:201], v153 offset:19456
	ds_read_b128 v[202:205], v153 offset:20480
	ds_read_b128 v[206:209], v153 offset:21504
	ds_read_b128 v[210:213], v153 offset:22528
	ds_read_b128 v[214:217], v153 offset:23552
	s_waitcnt vmcnt(8)
	s_waitcnt lgkmcnt(0)
	s_barrier
	v_mfma_f32_16x16x32_bf16 v[60:63], v[154:157], v[186:189], v[60:63]
	v_mfma_f32_16x16x32_bf16 v[60:63], v[158:161], v[190:193], v[60:63]
	v_mfma_f32_16x16x32_bf16 v[56:59], v[166:169], v[190:193], v[56:59]
	v_mfma_f32_16x16x32_bf16 v[56:59], v[162:165], v[186:189], v[56:59]
	v_mfma_f32_16x16x32_bf16 v[52:55], v[170:173], v[186:189], v[52:55]
	v_mfma_f32_16x16x32_bf16 v[52:55], v[174:177], v[190:193], v[52:55]
	v_mfma_f32_16x16x32_bf16 v[48:51], v[182:185], v[190:193], v[48:51]
	v_mfma_f32_16x16x32_bf16 v[48:51], v[178:181], v[186:189], v[48:51]
	v_mfma_f32_16x16x32_bf16 v[32:35], v[178:181], v[194:197], v[32:35]
	v_mfma_f32_16x16x32_bf16 v[32:35], v[182:185], v[198:201], v[32:35]
	v_mfma_f32_16x16x32_bf16 v[36:39], v[174:177], v[198:201], v[36:39]
	v_mfma_f32_16x16x32_bf16 v[36:39], v[170:173], v[194:197], v[36:39]
	v_mfma_f32_16x16x32_bf16 v[40:43], v[162:165], v[194:197], v[40:43]
	v_mfma_f32_16x16x32_bf16 v[40:43], v[166:169], v[198:201], v[40:43]
	v_mfma_f32_16x16x32_bf16 v[44:47], v[158:161], v[198:201], v[44:47]
	v_mfma_f32_16x16x32_bf16 v[44:47], v[154:157], v[194:197], v[44:47]
	v_mfma_f32_16x16x32_bf16 v[28:31], v[154:157], v[202:205], v[28:31]
	v_mfma_f32_16x16x32_bf16 v[28:31], v[158:161], v[206:209], v[28:31]
	v_mfma_f32_16x16x32_bf16 v[24:27], v[166:169], v[206:209], v[24:27]
	v_mfma_f32_16x16x32_bf16 v[24:27], v[162:165], v[202:205], v[24:27]
	v_mfma_f32_16x16x32_bf16 v[20:23], v[170:173], v[202:205], v[20:23]
	v_mfma_f32_16x16x32_bf16 v[20:23], v[174:177], v[206:209], v[20:23]
	v_mfma_f32_16x16x32_bf16 v[16:19], v[182:185], v[206:209], v[16:19]
	v_mfma_f32_16x16x32_bf16 v[16:19], v[178:181], v[202:205], v[16:19]
	v_mfma_f32_16x16x32_bf16 v[0:3], v[178:181], v[210:213], v[0:3]
	v_mfma_f32_16x16x32_bf16 v[0:3], v[182:185], v[214:217], v[0:3]
	v_mfma_f32_16x16x32_bf16 v[4:7], v[174:177], v[214:217], v[4:7]
	v_mfma_f32_16x16x32_bf16 v[4:7], v[170:173], v[210:213], v[4:7]
	v_mfma_f32_16x16x32_bf16 v[8:11], v[162:165], v[210:213], v[8:11]
	v_mfma_f32_16x16x32_bf16 v[8:11], v[166:169], v[214:217], v[8:11]
	v_mfma_f32_16x16x32_bf16 v[12:15], v[158:161], v[214:217], v[12:15]
	v_mfma_f32_16x16x32_bf16 v[12:15], v[154:157], v[210:213], v[12:15]
	s_barrier
	s_add_i32 s59, 0, 0x18000
	s_add_i32 s60, 0, 0x1c000
	v_add_u32_e32 v166, s59, v152
	v_add_u32_e32 v182, s60, v152
	ds_read_b128 v[154:157], v166
	ds_read_b128 v[158:161], v166 offset:1024
	ds_read_b128 v[162:165], v166 offset:2048
	ds_read_b128 v[166:169], v166 offset:3072
	ds_read_b128 v[170:173], v182
	ds_read_b128 v[174:177], v182 offset:1024
	ds_read_b128 v[178:181], v182 offset:2048
	ds_read_b128 v[182:185], v182 offset:3072
	s_add_u32 s34, s34, 0x100000
	s_addc_u32 s35, s35, 0
	s_mov_b32 m0, s46
	v_lshl_add_u64 v[186:187], s[34:35], 0, v[128:129]
	global_load_lds_dwordx4 v[186:187], off
	v_lshl_add_u64 v[186:187], s[34:35], 0, v[132:133]
	s_mov_b32 m0, s47
	s_nop 0
	global_load_lds_dwordx4 v[186:187], off
	ds_read_b128 v[186:189], v153 offset:32768
	ds_read_b128 v[190:193], v153 offset:33792
	ds_read_b128 v[194:197], v153 offset:34816
	ds_read_b128 v[198:201], v153 offset:35840
	ds_read_b128 v[202:205], v153 offset:36864
	ds_read_b128 v[206:209], v153 offset:37888
	ds_read_b128 v[210:213], v153 offset:38912
	ds_read_b128 v[214:217], v153 offset:39936
	s_waitcnt vmcnt(8)
	s_waitcnt lgkmcnt(0)
	s_barrier
	v_mfma_f32_16x16x32_bf16 v[124:127], v[154:157], v[186:189], v[124:127]
	v_mfma_f32_16x16x32_bf16 v[124:127], v[158:161], v[190:193], v[124:127]
	v_mfma_f32_16x16x32_bf16 v[120:123], v[166:169], v[190:193], v[120:123]
	v_mfma_f32_16x16x32_bf16 v[120:123], v[162:165], v[186:189], v[120:123]
	v_mfma_f32_16x16x32_bf16 v[116:119], v[170:173], v[186:189], v[116:119]
	v_mfma_f32_16x16x32_bf16 v[116:119], v[174:177], v[190:193], v[116:119]
	v_mfma_f32_16x16x32_bf16 v[112:115], v[182:185], v[190:193], v[112:115]
	v_mfma_f32_16x16x32_bf16 v[112:115], v[178:181], v[186:189], v[112:115]
	v_mfma_f32_16x16x32_bf16 v[96:99], v[178:181], v[194:197], v[96:99]
	v_mfma_f32_16x16x32_bf16 v[96:99], v[182:185], v[198:201], v[96:99]
	v_mfma_f32_16x16x32_bf16 v[100:103], v[174:177], v[198:201], v[100:103]
	v_mfma_f32_16x16x32_bf16 v[100:103], v[170:173], v[194:197], v[100:103]
	v_mfma_f32_16x16x32_bf16 v[104:107], v[162:165], v[194:197], v[104:107]
	v_mfma_f32_16x16x32_bf16 v[104:107], v[166:169], v[198:201], v[104:107]
	v_mfma_f32_16x16x32_bf16 v[108:111], v[158:161], v[198:201], v[108:111]
	v_mfma_f32_16x16x32_bf16 v[108:111], v[154:157], v[194:197], v[108:111]
	v_mfma_f32_16x16x32_bf16 v[92:95], v[154:157], v[202:205], v[92:95]
	v_mfma_f32_16x16x32_bf16 v[92:95], v[158:161], v[206:209], v[92:95]
	v_mfma_f32_16x16x32_bf16 v[88:91], v[166:169], v[206:209], v[88:91]
	v_mfma_f32_16x16x32_bf16 v[88:91], v[162:165], v[202:205], v[88:91]
	v_mfma_f32_16x16x32_bf16 v[84:87], v[170:173], v[202:205], v[84:87]
	v_mfma_f32_16x16x32_bf16 v[84:87], v[174:177], v[206:209], v[84:87]
	v_mfma_f32_16x16x32_bf16 v[80:83], v[182:185], v[206:209], v[80:83]
	v_mfma_f32_16x16x32_bf16 v[80:83], v[178:181], v[202:205], v[80:83]
	v_mfma_f32_16x16x32_bf16 v[64:67], v[178:181], v[210:213], v[64:67]
	v_mfma_f32_16x16x32_bf16 v[64:67], v[182:185], v[214:217], v[64:67]
	v_mfma_f32_16x16x32_bf16 v[68:71], v[174:177], v[214:217], v[68:71]
	v_mfma_f32_16x16x32_bf16 v[68:71], v[170:173], v[210:213], v[68:71]
	v_mfma_f32_16x16x32_bf16 v[72:75], v[162:165], v[210:213], v[72:75]
	v_mfma_f32_16x16x32_bf16 v[72:75], v[166:169], v[214:217], v[72:75]
	v_mfma_f32_16x16x32_bf16 v[76:79], v[158:161], v[214:217], v[76:79]
	v_mfma_f32_16x16x32_bf16 v[76:79], v[154:157], v[210:213], v[76:79]
	s_barrier
	s_add_i32 s34, s59, s43
	v_lshl_add_u64 v[186:187], v[218:219], 0, s[14:15]
	s_mov_b32 m0, s34
	s_nop 0
	global_load_lds_dwordx4 v[186:187], off
	s_add_i32 m0, s34, 0x2000
	s_add_u32 s30, s30, 0x100080
	v_lshl_add_u64 v[186:187], v[220:221], 0, s[14:15]
	s_addc_u32 s31, s31, 0
	s_add_i32 s34, s60, s43
	global_load_lds_dwordx4 v[186:187], off
	v_lshl_add_u64 v[186:187], s[30:31], 0, v[130:131]
	s_mov_b32 m0, s34
	s_nop 0
	global_load_lds_dwordx4 v[186:187], off
	v_lshl_add_u64 v[186:187], s[30:31], 0, v[134:135]
	s_add_i32 m0, s34, 0x2000
	s_nop 0
	global_load_lds_dwordx4 v[186:187], off
	v_lshl_add_u64 v[186:187], v[222:223], 0, s[16:17]
	s_mov_b32 m0, s49
	s_nop 0
	global_load_lds_dwordx4 v[186:187], off
	v_lshl_add_u64 v[186:187], v[224:225], 0, s[16:17]
	s_mov_b32 m0, s50
	s_nop 0
	global_load_lds_dwordx4 v[186:187], off
	ds_read_b128 v[186:189], v153 offset:49152
	ds_read_b128 v[190:193], v153 offset:50176
	ds_read_b128 v[194:197], v153 offset:51200
	ds_read_b128 v[198:201], v153 offset:52224
	ds_read_b128 v[202:205], v153 offset:53248
	ds_read_b128 v[206:209], v153 offset:54272
	ds_read_b128 v[210:213], v153 offset:55296
	ds_read_b128 v[214:217], v153 offset:56320
	s_waitcnt vmcnt(8)
	s_waitcnt lgkmcnt(0)
	s_barrier
	v_mfma_f32_16x16x32_bf16 v[60:63], v[154:157], v[186:189], v[60:63]
	v_mfma_f32_16x16x32_bf16 v[60:63], v[158:161], v[190:193], v[60:63]
	v_mfma_f32_16x16x32_bf16 v[56:59], v[166:169], v[190:193], v[56:59]
	v_mfma_f32_16x16x32_bf16 v[56:59], v[162:165], v[186:189], v[56:59]
	v_mfma_f32_16x16x32_bf16 v[52:55], v[170:173], v[186:189], v[52:55]
	v_mfma_f32_16x16x32_bf16 v[52:55], v[174:177], v[190:193], v[52:55]
	v_mfma_f32_16x16x32_bf16 v[48:51], v[182:185], v[190:193], v[48:51]
	v_mfma_f32_16x16x32_bf16 v[48:51], v[178:181], v[186:189], v[48:51]
	v_mfma_f32_16x16x32_bf16 v[32:35], v[178:181], v[194:197], v[32:35]
	v_mfma_f32_16x16x32_bf16 v[32:35], v[182:185], v[198:201], v[32:35]
	v_mfma_f32_16x16x32_bf16 v[36:39], v[174:177], v[198:201], v[36:39]
	v_mfma_f32_16x16x32_bf16 v[36:39], v[170:173], v[194:197], v[36:39]
	v_mfma_f32_16x16x32_bf16 v[40:43], v[162:165], v[194:197], v[40:43]
	v_mfma_f32_16x16x32_bf16 v[40:43], v[166:169], v[198:201], v[40:43]
	v_mfma_f32_16x16x32_bf16 v[44:47], v[158:161], v[198:201], v[44:47]
	v_mfma_f32_16x16x32_bf16 v[44:47], v[154:157], v[194:197], v[44:47]
	v_mfma_f32_16x16x32_bf16 v[28:31], v[154:157], v[202:205], v[28:31]
	v_mfma_f32_16x16x32_bf16 v[28:31], v[158:161], v[206:209], v[28:31]
	v_mfma_f32_16x16x32_bf16 v[24:27], v[166:169], v[206:209], v[24:27]
	v_mfma_f32_16x16x32_bf16 v[24:27], v[162:165], v[202:205], v[24:27]
	v_mfma_f32_16x16x32_bf16 v[20:23], v[170:173], v[202:205], v[20:23]
	v_mfma_f32_16x16x32_bf16 v[20:23], v[174:177], v[206:209], v[20:23]
	v_mfma_f32_16x16x32_bf16 v[16:19], v[182:185], v[206:209], v[16:19]
	v_mfma_f32_16x16x32_bf16 v[16:19], v[178:181], v[202:205], v[16:19]
	v_mfma_f32_16x16x32_bf16 v[0:3], v[178:181], v[210:213], v[0:3]
	v_mfma_f32_16x16x32_bf16 v[0:3], v[182:185], v[214:217], v[0:3]
	v_mfma_f32_16x16x32_bf16 v[4:7], v[174:177], v[214:217], v[4:7]
	v_mfma_f32_16x16x32_bf16 v[4:7], v[170:173], v[210:213], v[4:7]
	v_mfma_f32_16x16x32_bf16 v[8:11], v[162:165], v[210:213], v[8:11]
	v_mfma_f32_16x16x32_bf16 v[8:11], v[166:169], v[214:217], v[8:11]
	v_mfma_f32_16x16x32_bf16 v[12:15], v[158:161], v[214:217], v[12:15]
	v_mfma_f32_16x16x32_bf16 v[12:15], v[154:157], v[210:213], v[12:15]
	s_barrier
	s_add_i32 s58, s58, 2
	s_add_u32 s56, s56, 0x100
	s_addc_u32 s57, s57, 0
	s_add_u32 s28, s28, 0x1000
	s_addc_u32 s29, s29, 0
	v_lshl_add_u64 v[146:147], v[146:147], 0, s[18:19]
	s_cmp_gt_u32 s58, 61
	v_lshl_add_u64 v[144:145], v[144:145], 0, s[18:19]
	s_cbranch_scc0 .LBB0_1340
	s_andn2_b64 vcc, exec, s[4:5]
	s_cbranch_vccnz .LBB0_1332
	v_mov_b32_e32 v0, 0
	s_mov_b32 s7, s20
	s_mov_b32 s6, s22
	s_mov_b64 s[8:9], s[26:27]
	s_mov_b64 s[10:11], s[24:25]
	s_mov_b32 s48, s53
	v_mov_b32_e32 v1, v0
	v_mov_b32_e32 v2, v0
	v_mov_b32_e32 v3, v0
	v_mov_b32_e32 v4, v0
	v_mov_b32_e32 v5, v0
	v_mov_b32_e32 v6, v0
	v_mov_b32_e32 v7, v0
	v_mov_b32_e32 v16, v0
	v_mov_b32_e32 v17, v0
	v_mov_b32_e32 v18, v0
	v_mov_b32_e32 v19, v0
	v_mov_b32_e32 v20, v0
	v_mov_b32_e32 v21, v0
	v_mov_b32_e32 v22, v0
	v_mov_b32_e32 v23, v0
	v_mov_b32_e32 v32, v0
	v_mov_b32_e32 v33, v0
	v_mov_b32_e32 v34, v0
	v_mov_b32_e32 v35, v0
	v_mov_b32_e32 v36, v0
	v_mov_b32_e32 v37, v0
	v_mov_b32_e32 v38, v0
	v_mov_b32_e32 v39, v0
	v_mov_b32_e32 v48, v0
	v_mov_b32_e32 v49, v0
	v_mov_b32_e32 v50, v0
	v_mov_b32_e32 v51, v0
	v_mov_b32_e32 v52, v0
	v_mov_b32_e32 v53, v0
	v_mov_b32_e32 v54, v0
	v_mov_b32_e32 v55, v0
	v_mov_b32_e32 v8, v0
	v_mov_b32_e32 v9, v0
	v_mov_b32_e32 v10, v0
	v_mov_b32_e32 v11, v0
	v_mov_b32_e32 v12, v0
	v_mov_b32_e32 v13, v0
	v_mov_b32_e32 v14, v0
	v_mov_b32_e32 v15, v0
	v_mov_b32_e32 v24, v0
	v_mov_b32_e32 v25, v0
	v_mov_b32_e32 v26, v0
	v_mov_b32_e32 v27, v0
	v_mov_b32_e32 v28, v0
	v_mov_b32_e32 v29, v0
	v_mov_b32_e32 v30, v0
	v_mov_b32_e32 v31, v0
	v_mov_b32_e32 v40, v0
	v_mov_b32_e32 v41, v0
	v_mov_b32_e32 v42, v0
	v_mov_b32_e32 v43, v0
	v_mov_b32_e32 v44, v0
	v_mov_b32_e32 v45, v0
	v_mov_b32_e32 v46, v0
	v_mov_b32_e32 v47, v0
	v_mov_b32_e32 v56, v0
	v_mov_b32_e32 v57, v0
	v_mov_b32_e32 v58, v0
	v_mov_b32_e32 v59, v0
	v_mov_b32_e32 v60, v0
	v_mov_b32_e32 v61, v0
	v_mov_b32_e32 v62, v0
	v_mov_b32_e32 v63, v0
	v_mov_b32_e32 v64, v0
	v_mov_b32_e32 v65, v0
	v_mov_b32_e32 v66, v0
	v_mov_b32_e32 v67, v0
	v_mov_b32_e32 v68, v0
	v_mov_b32_e32 v69, v0
	v_mov_b32_e32 v70, v0
	v_mov_b32_e32 v71, v0
	v_mov_b32_e32 v80, v0
	v_mov_b32_e32 v81, v0
	v_mov_b32_e32 v82, v0
	v_mov_b32_e32 v83, v0
	v_mov_b32_e32 v84, v0
	v_mov_b32_e32 v85, v0
	v_mov_b32_e32 v86, v0
	v_mov_b32_e32 v87, v0
	v_mov_b32_e32 v96, v0
	v_mov_b32_e32 v97, v0
	v_mov_b32_e32 v98, v0
	v_mov_b32_e32 v99, v0
	v_mov_b32_e32 v100, v0
	v_mov_b32_e32 v101, v0
	v_mov_b32_e32 v102, v0
	v_mov_b32_e32 v103, v0
	v_mov_b32_e32 v112, v0
	v_mov_b32_e32 v113, v0
	v_mov_b32_e32 v114, v0
	v_mov_b32_e32 v115, v0
	v_mov_b32_e32 v116, v0
	v_mov_b32_e32 v117, v0
	v_mov_b32_e32 v118, v0
	v_mov_b32_e32 v119, v0
	v_mov_b32_e32 v72, v0
	v_mov_b32_e32 v73, v0
	v_mov_b32_e32 v74, v0
	v_mov_b32_e32 v75, v0
	v_mov_b32_e32 v76, v0
	v_mov_b32_e32 v77, v0
	v_mov_b32_e32 v78, v0
	v_mov_b32_e32 v79, v0
	v_mov_b32_e32 v88, v0
	v_mov_b32_e32 v89, v0
	v_mov_b32_e32 v90, v0
	v_mov_b32_e32 v91, v0
	v_mov_b32_e32 v92, v0
	v_mov_b32_e32 v93, v0
	v_mov_b32_e32 v94, v0
	v_mov_b32_e32 v95, v0
	v_mov_b32_e32 v104, v0
	v_mov_b32_e32 v105, v0
	v_mov_b32_e32 v106, v0
	v_mov_b32_e32 v107, v0
	v_mov_b32_e32 v108, v0
	v_mov_b32_e32 v109, v0
	v_mov_b32_e32 v110, v0
	v_mov_b32_e32 v111, v0
	v_mov_b32_e32 v120, v0
	v_mov_b32_e32 v121, v0
	v_mov_b32_e32 v122, v0
	v_mov_b32_e32 v123, v0
	v_mov_b32_e32 v124, v0
	v_mov_b32_e32 v125, v0
	v_mov_b32_e32 v126, v0
	v_mov_b32_e32 v127, v0
	s_branch .LBB0_1332

.LBB0_1435:
	ds_read_b128 v[128:131], v180
	ds_read_b128 v[132:135], v180 offset:1024
	ds_read_b128 v[136:139], v180 offset:2048
	ds_read_b128 v[140:143], v180 offset:3072
	ds_read_b128 v[144:147], v181
	ds_read_b128 v[148:151], v181 offset:1024
	ds_read_b128 v[170:173], v181 offset:2048
	ds_read_b128 v[174:177], v181 offset:3072
	s_add_u32 s26, s24, 0xfffc0080
	s_addc_u32 s27, s25, -1
	s_cmp_eq_u32 s35, 12
	s_cselect_b32 s29, s1, s27
	s_cselect_b32 s28, s19, s26
	s_cselect_b32 s27, s17, s34
	s_cselect_b32 s26, s30, s31
	v_lshl_add_u64 v[184:185], s[24:25], 0, v[162:163]
	s_add_i32 m0, s40, 0xc000
	s_nop 0
	global_load_lds_dwordx4 v[184:185], off
	v_lshl_add_u64 v[184:185], s[24:25], 0, v[164:165]
	s_add_i32 m0, s40, 0xe000
	s_nop 0
	global_load_lds_dwordx4 v[184:185], off
	ds_read_b128 v[184:187], v182
	ds_read_b128 v[188:191], v182 offset:1024
	ds_read_b128 v[192:195], v182 offset:2048
	ds_read_b128 v[196:199], v182 offset:3072
	ds_read_b128 v[200:203], v182 offset:4096
	ds_read_b128 v[204:207], v182 offset:5120
	ds_read_b128 v[208:211], v182 offset:6144
	ds_read_b128 v[212:215], v182 offset:7168
	s_waitcnt vmcnt(8)
	s_waitcnt lgkmcnt(0)
	s_barrier
	v_mfma_f32_16x16x32_bf16 v[124:127], v[128:131], v[184:187], v[124:127]
	v_mfma_f32_16x16x32_bf16 v[124:127], v[132:135], v[188:191], v[124:127]
	v_mfma_f32_16x16x32_bf16 v[120:123], v[140:143], v[188:191], v[120:123]
	v_mfma_f32_16x16x32_bf16 v[120:123], v[136:139], v[184:187], v[120:123]
	v_mfma_f32_16x16x32_bf16 v[116:119], v[144:147], v[184:187], v[116:119]
	v_mfma_f32_16x16x32_bf16 v[116:119], v[148:151], v[188:191], v[116:119]
	v_mfma_f32_16x16x32_bf16 v[112:115], v[174:177], v[188:191], v[112:115]
	v_mfma_f32_16x16x32_bf16 v[112:115], v[170:173], v[184:187], v[112:115]
	v_mfma_f32_16x16x32_bf16 v[96:99], v[170:173], v[192:195], v[96:99]
	v_mfma_f32_16x16x32_bf16 v[96:99], v[174:177], v[196:199], v[96:99]
	v_mfma_f32_16x16x32_bf16 v[100:103], v[148:151], v[196:199], v[100:103]
	v_mfma_f32_16x16x32_bf16 v[100:103], v[144:147], v[192:195], v[100:103]
	v_mfma_f32_16x16x32_bf16 v[104:107], v[136:139], v[192:195], v[104:107]
	v_mfma_f32_16x16x32_bf16 v[104:107], v[140:143], v[196:199], v[104:107]
	v_mfma_f32_16x16x32_bf16 v[108:111], v[132:135], v[196:199], v[108:111]
	v_mfma_f32_16x16x32_bf16 v[108:111], v[128:131], v[192:195], v[108:111]
	v_mfma_f32_16x16x32_bf16 v[92:95], v[128:131], v[200:203], v[92:95]
	v_mfma_f32_16x16x32_bf16 v[92:95], v[132:135], v[204:207], v[92:95]
	v_mfma_f32_16x16x32_bf16 v[88:91], v[140:143], v[204:207], v[88:91]
	v_mfma_f32_16x16x32_bf16 v[88:91], v[136:139], v[200:203], v[88:91]
	v_mfma_f32_16x16x32_bf16 v[84:87], v[144:147], v[200:203], v[84:87]
	v_mfma_f32_16x16x32_bf16 v[84:87], v[148:151], v[204:207], v[84:87]
	v_mfma_f32_16x16x32_bf16 v[80:83], v[174:177], v[204:207], v[80:83]
	v_mfma_f32_16x16x32_bf16 v[80:83], v[170:173], v[200:203], v[80:83]
	v_mfma_f32_16x16x32_bf16 v[64:67], v[170:173], v[208:211], v[64:67]
	v_mfma_f32_16x16x32_bf16 v[64:67], v[174:177], v[212:215], v[64:67]
	v_mfma_f32_16x16x32_bf16 v[68:71], v[148:151], v[212:215], v[68:71]
	v_mfma_f32_16x16x32_bf16 v[68:71], v[144:147], v[208:211], v[68:71]
	v_mfma_f32_16x16x32_bf16 v[72:75], v[136:139], v[208:211], v[72:75]
	v_mfma_f32_16x16x32_bf16 v[72:75], v[140:143], v[212:215], v[72:75]
	v_mfma_f32_16x16x32_bf16 v[76:79], v[132:135], v[212:215], v[76:79]
	v_mfma_f32_16x16x32_bf16 v[76:79], v[128:131], v[208:211], v[76:79]
	s_barrier
	s_add_i32 s54, s50, s39
	v_lshl_add_u64 v[216:217], s[26:27], 0, v[154:155]
	s_mov_b32 m0, s54
	v_lshl_add_u64 v[218:219], s[26:27], 0, v[158:159]
	global_load_lds_dwordx4 v[216:217], off
	s_add_i32 m0, s54, 0x2000
	s_add_u32 s54, s26, 0x100000
	s_addc_u32 s55, s27, 0
	s_add_i32 s56, s51, s39
	global_load_lds_dwordx4 v[218:219], off
	v_lshl_add_u64 v[184:185], s[54:55], 0, v[154:155]
	s_mov_b32 m0, s56
	v_lshl_add_u64 v[220:221], s[28:29], 0, v[152:153]
	global_load_lds_dwordx4 v[184:185], off
	v_lshl_add_u64 v[184:185], s[54:55], 0, v[158:159]
	s_add_i32 m0, s56, 0x2000
	v_lshl_add_u64 v[222:223], s[28:29], 0, v[156:157]
	global_load_lds_dwordx4 v[184:185], off
	s_mov_b32 m0, s40
	s_nop 0
	global_load_lds_dwordx4 v[220:221], off
	s_mov_b32 m0, s41
	s_nop 0
	global_load_lds_dwordx4 v[222:223], off
	ds_read_b128 v[184:187], v182 offset:16384
	ds_read_b128 v[188:191], v182 offset:17408
	ds_read_b128 v[192:195], v182 offset:18432
	ds_read_b128 v[196:199], v182 offset:19456
	ds_read_b128 v[200:203], v182 offset:20480
	ds_read_b128 v[204:207], v182 offset:21504
	ds_read_b128 v[208:211], v182 offset:22528
	ds_read_b128 v[212:215], v182 offset:23552
	s_waitcnt vmcnt(8)
	s_waitcnt lgkmcnt(0)
	s_barrier
	v_mfma_f32_16x16x32_bf16 v[60:63], v[128:131], v[184:187], v[60:63]
	v_mfma_f32_16x16x32_bf16 v[60:63], v[132:135], v[188:191], v[60:63]
	v_mfma_f32_16x16x32_bf16 v[56:59], v[140:143], v[188:191], v[56:59]
	v_mfma_f32_16x16x32_bf16 v[56:59], v[136:139], v[184:187], v[56:59]
	v_mfma_f32_16x16x32_bf16 v[52:55], v[144:147], v[184:187], v[52:55]
	v_mfma_f32_16x16x32_bf16 v[52:55], v[148:151], v[188:191], v[52:55]
	v_mfma_f32_16x16x32_bf16 v[48:51], v[174:177], v[188:191], v[48:51]
	v_mfma_f32_16x16x32_bf16 v[48:51], v[170:173], v[184:187], v[48:51]
	v_mfma_f32_16x16x32_bf16 v[32:35], v[170:173], v[192:195], v[32:35]
	v_mfma_f32_16x16x32_bf16 v[32:35], v[174:177], v[196:199], v[32:35]
	v_mfma_f32_16x16x32_bf16 v[36:39], v[148:151], v[196:199], v[36:39]
	v_mfma_f32_16x16x32_bf16 v[36:39], v[144:147], v[192:195], v[36:39]
	v_mfma_f32_16x16x32_bf16 v[40:43], v[136:139], v[192:195], v[40:43]
	v_mfma_f32_16x16x32_bf16 v[40:43], v[140:143], v[196:199], v[40:43]
	v_mfma_f32_16x16x32_bf16 v[44:47], v[132:135], v[196:199], v[44:47]
	v_mfma_f32_16x16x32_bf16 v[44:47], v[128:131], v[192:195], v[44:47]
	v_mfma_f32_16x16x32_bf16 v[28:31], v[128:131], v[200:203], v[28:31]
	v_mfma_f32_16x16x32_bf16 v[28:31], v[132:135], v[204:207], v[28:31]
	v_mfma_f32_16x16x32_bf16 v[24:27], v[140:143], v[204:207], v[24:27]
	v_mfma_f32_16x16x32_bf16 v[24:27], v[136:139], v[200:203], v[24:27]
	v_mfma_f32_16x16x32_bf16 v[20:23], v[144:147], v[200:203], v[20:23]
	v_mfma_f32_16x16x32_bf16 v[20:23], v[148:151], v[204:207], v[20:23]
	v_mfma_f32_16x16x32_bf16 v[16:19], v[174:177], v[204:207], v[16:19]
	v_mfma_f32_16x16x32_bf16 v[16:19], v[170:173], v[200:203], v[16:19]
	v_mfma_f32_16x16x32_bf16 v[0:3], v[170:173], v[208:211], v[0:3]
	v_mfma_f32_16x16x32_bf16 v[0:3], v[174:177], v[212:215], v[0:3]
	v_mfma_f32_16x16x32_bf16 v[4:7], v[148:151], v[212:215], v[4:7]
	v_mfma_f32_16x16x32_bf16 v[4:7], v[144:147], v[208:211], v[4:7]
	v_mfma_f32_16x16x32_bf16 v[8:11], v[136:139], v[208:211], v[8:11]
	v_mfma_f32_16x16x32_bf16 v[8:11], v[140:143], v[212:215], v[8:11]
	v_mfma_f32_16x16x32_bf16 v[12:15], v[132:135], v[212:215], v[12:15]
	v_mfma_f32_16x16x32_bf16 v[12:15], v[128:131], v[208:211], v[12:15]
	s_barrier
	s_add_i32 s54, 0, 0x18000
	s_add_i32 s55, 0, 0x1c000
	v_add_u32_e32 v140, s54, v178
	v_add_u32_e32 v174, s55, v178
	ds_read_b128 v[128:131], v140
	ds_read_b128 v[132:135], v140 offset:1024
	ds_read_b128 v[136:139], v140 offset:2048
	ds_read_b128 v[140:143], v140 offset:3072
	ds_read_b128 v[144:147], v174
	ds_read_b128 v[148:151], v174 offset:1024
	ds_read_b128 v[170:173], v174 offset:2048
	ds_read_b128 v[174:177], v174 offset:3072
	s_add_u32 s28, s28, 0x40000
	s_addc_u32 s29, s29, 0
	s_mov_b32 m0, s42
	v_lshl_add_u64 v[184:185], s[28:29], 0, v[152:153]
	global_load_lds_dwordx4 v[184:185], off
	v_lshl_add_u64 v[184:185], s[28:29], 0, v[156:157]
	s_mov_b32 m0, s43
	s_nop 0
	global_load_lds_dwordx4 v[184:185], off
	ds_read_b128 v[184:187], v182 offset:32768
	ds_read_b128 v[188:191], v182 offset:33792
	ds_read_b128 v[192:195], v182 offset:34816
	ds_read_b128 v[196:199], v182 offset:35840
	ds_read_b128 v[200:203], v182 offset:36864
	ds_read_b128 v[204:207], v182 offset:37888
	ds_read_b128 v[208:211], v182 offset:38912
	ds_read_b128 v[212:215], v182 offset:39936
	s_waitcnt vmcnt(8)
	s_waitcnt lgkmcnt(0)
	s_barrier
	v_mfma_f32_16x16x32_bf16 v[124:127], v[128:131], v[184:187], v[124:127]
	v_mfma_f32_16x16x32_bf16 v[124:127], v[132:135], v[188:191], v[124:127]
	v_mfma_f32_16x16x32_bf16 v[120:123], v[140:143], v[188:191], v[120:123]
	v_mfma_f32_16x16x32_bf16 v[120:123], v[136:139], v[184:187], v[120:123]
	v_mfma_f32_16x16x32_bf16 v[116:119], v[144:147], v[184:187], v[116:119]
	v_mfma_f32_16x16x32_bf16 v[116:119], v[148:151], v[188:191], v[116:119]
	v_mfma_f32_16x16x32_bf16 v[112:115], v[174:177], v[188:191], v[112:115]
	v_mfma_f32_16x16x32_bf16 v[112:115], v[170:173], v[184:187], v[112:115]
	v_mfma_f32_16x16x32_bf16 v[96:99], v[170:173], v[192:195], v[96:99]
	v_mfma_f32_16x16x32_bf16 v[96:99], v[174:177], v[196:199], v[96:99]
	v_mfma_f32_16x16x32_bf16 v[100:103], v[148:151], v[196:199], v[100:103]
	v_mfma_f32_16x16x32_bf16 v[100:103], v[144:147], v[192:195], v[100:103]
	v_mfma_f32_16x16x32_bf16 v[104:107], v[136:139], v[192:195], v[104:107]
	v_mfma_f32_16x16x32_bf16 v[104:107], v[140:143], v[196:199], v[104:107]
	v_mfma_f32_16x16x32_bf16 v[108:111], v[132:135], v[196:199], v[108:111]
	v_mfma_f32_16x16x32_bf16 v[108:111], v[128:131], v[192:195], v[108:111]
	v_mfma_f32_16x16x32_bf16 v[92:95], v[128:131], v[200:203], v[92:95]
	v_mfma_f32_16x16x32_bf16 v[92:95], v[132:135], v[204:207], v[92:95]
	v_mfma_f32_16x16x32_bf16 v[88:91], v[140:143], v[204:207], v[88:91]
	v_mfma_f32_16x16x32_bf16 v[88:91], v[136:139], v[200:203], v[88:91]
	v_mfma_f32_16x16x32_bf16 v[84:87], v[144:147], v[200:203], v[84:87]
	v_mfma_f32_16x16x32_bf16 v[84:87], v[148:151], v[204:207], v[84:87]
	v_mfma_f32_16x16x32_bf16 v[80:83], v[174:177], v[204:207], v[80:83]
	v_mfma_f32_16x16x32_bf16 v[80:83], v[170:173], v[200:203], v[80:83]
	v_mfma_f32_16x16x32_bf16 v[64:67], v[170:173], v[208:211], v[64:67]
	v_mfma_f32_16x16x32_bf16 v[64:67], v[174:177], v[212:215], v[64:67]
	v_mfma_f32_16x16x32_bf16 v[68:71], v[148:151], v[212:215], v[68:71]
	v_mfma_f32_16x16x32_bf16 v[68:71], v[144:147], v[208:211], v[68:71]
	v_mfma_f32_16x16x32_bf16 v[72:75], v[136:139], v[208:211], v[72:75]
	v_mfma_f32_16x16x32_bf16 v[72:75], v[140:143], v[212:215], v[72:75]
	v_mfma_f32_16x16x32_bf16 v[76:79], v[132:135], v[212:215], v[76:79]
	v_mfma_f32_16x16x32_bf16 v[76:79], v[128:131], v[208:211], v[76:79]
	s_barrier
	s_add_i32 s28, s54, s39
	v_lshl_add_u64 v[184:185], v[216:217], 0, s[14:15]
	s_mov_b32 m0, s28
	s_nop 0
	global_load_lds_dwordx4 v[184:185], off
	s_add_i32 m0, s28, 0x2000
	s_add_u32 s26, s26, 0x100080
	v_lshl_add_u64 v[184:185], v[218:219], 0, s[14:15]
	s_addc_u32 s27, s27, 0
	s_add_i32 s28, s55, s39
	global_load_lds_dwordx4 v[184:185], off
	v_lshl_add_u64 v[184:185], s[26:27], 0, v[154:155]
	s_mov_b32 m0, s28
	s_nop 0
	global_load_lds_dwordx4 v[184:185], off
	v_lshl_add_u64 v[184:185], s[26:27], 0, v[158:159]
	s_add_i32 m0, s28, 0x2000
	s_nop 0
	global_load_lds_dwordx4 v[184:185], off
	v_lshl_add_u64 v[184:185], v[220:221], 0, s[14:15]
	s_mov_b32 m0, s45
	s_nop 0
	global_load_lds_dwordx4 v[184:185], off
	v_lshl_add_u64 v[184:185], v[222:223], 0, s[14:15]
	s_mov_b32 m0, s46
	s_nop 0
	global_load_lds_dwordx4 v[184:185], off
	ds_read_b128 v[184:187], v182 offset:49152
	ds_read_b128 v[188:191], v182 offset:50176
	ds_read_b128 v[192:195], v182 offset:51200
	ds_read_b128 v[196:199], v182 offset:52224
	ds_read_b128 v[200:203], v182 offset:53248
	ds_read_b128 v[204:207], v182 offset:54272
	ds_read_b128 v[208:211], v182 offset:55296
	ds_read_b128 v[212:215], v182 offset:56320
	s_waitcnt vmcnt(8)
	s_waitcnt lgkmcnt(0)
	s_barrier
	v_mfma_f32_16x16x32_bf16 v[60:63], v[128:131], v[184:187], v[60:63]
	v_mfma_f32_16x16x32_bf16 v[60:63], v[132:135], v[188:191], v[60:63]
	v_mfma_f32_16x16x32_bf16 v[56:59], v[140:143], v[188:191], v[56:59]
	v_mfma_f32_16x16x32_bf16 v[56:59], v[136:139], v[184:187], v[56:59]
	v_mfma_f32_16x16x32_bf16 v[52:55], v[144:147], v[184:187], v[52:55]
	v_mfma_f32_16x16x32_bf16 v[52:55], v[148:151], v[188:191], v[52:55]
	v_mfma_f32_16x16x32_bf16 v[48:51], v[174:177], v[188:191], v[48:51]
	v_mfma_f32_16x16x32_bf16 v[48:51], v[170:173], v[184:187], v[48:51]
	v_mfma_f32_16x16x32_bf16 v[32:35], v[170:173], v[192:195], v[32:35]
	v_mfma_f32_16x16x32_bf16 v[32:35], v[174:177], v[196:199], v[32:35]
	v_mfma_f32_16x16x32_bf16 v[36:39], v[148:151], v[196:199], v[36:39]
	v_mfma_f32_16x16x32_bf16 v[36:39], v[144:147], v[192:195], v[36:39]
	v_mfma_f32_16x16x32_bf16 v[40:43], v[136:139], v[192:195], v[40:43]
	v_mfma_f32_16x16x32_bf16 v[40:43], v[140:143], v[196:199], v[40:43]
	v_mfma_f32_16x16x32_bf16 v[44:47], v[132:135], v[196:199], v[44:47]
	v_mfma_f32_16x16x32_bf16 v[44:47], v[128:131], v[192:195], v[44:47]
	v_mfma_f32_16x16x32_bf16 v[28:31], v[128:131], v[200:203], v[28:31]
	v_mfma_f32_16x16x32_bf16 v[28:31], v[132:135], v[204:207], v[28:31]
	v_mfma_f32_16x16x32_bf16 v[24:27], v[140:143], v[204:207], v[24:27]
	v_mfma_f32_16x16x32_bf16 v[24:27], v[136:139], v[200:203], v[24:27]
	v_mfma_f32_16x16x32_bf16 v[20:23], v[144:147], v[200:203], v[20:23]
	v_mfma_f32_16x16x32_bf16 v[20:23], v[148:151], v[204:207], v[20:23]
	v_mfma_f32_16x16x32_bf16 v[16:19], v[174:177], v[204:207], v[16:19]
	v_mfma_f32_16x16x32_bf16 v[16:19], v[170:173], v[200:203], v[16:19]
	v_mfma_f32_16x16x32_bf16 v[0:3], v[170:173], v[208:211], v[0:3]
	v_mfma_f32_16x16x32_bf16 v[0:3], v[174:177], v[212:215], v[0:3]
	v_mfma_f32_16x16x32_bf16 v[4:7], v[148:151], v[212:215], v[4:7]
	v_mfma_f32_16x16x32_bf16 v[4:7], v[144:147], v[208:211], v[4:7]
	v_mfma_f32_16x16x32_bf16 v[8:11], v[136:139], v[208:211], v[8:11]
	v_mfma_f32_16x16x32_bf16 v[8:11], v[140:143], v[212:215], v[8:11]
	v_mfma_f32_16x16x32_bf16 v[12:15], v[132:135], v[212:215], v[12:15]
	v_mfma_f32_16x16x32_bf16 v[12:15], v[128:131], v[208:211], v[12:15]
	s_barrier
	s_add_i32 s35, s35, 2
	s_add_u32 s24, s24, 0x100
	s_addc_u32 s25, s25, 0
	s_add_u32 s31, s31, 0x100
	s_addc_u32 s34, s34, 0
	s_cmp_gt_u32 s35, 13
	s_cbranch_scc0 .LBB0_1435

.LBB0_1543:
	ds_read_b128 v[128:131], v167
	ds_read_b128 v[154:157], v167 offset:1024
	ds_read_b128 v[172:175], v167 offset:2048
	ds_read_b128 v[176:179], v167 offset:3072
	ds_read_b128 v[180:183], v168
	ds_read_b128 v[184:187], v168 offset:1024
	ds_read_b128 v[188:191], v168 offset:2048
	ds_read_b128 v[192:195], v168 offset:3072
	s_add_u32 s22, s20, 0x1000
	s_addc_u32 s23, s21, 0
	s_cmp_eq_u32 s54, 60
	s_cselect_b32 s27, s13, s23
	s_cselect_b32 s26, s50, s22
	s_cselect_b32 s25, s11, s53
	s_cselect_b32 s24, s51, s52
	v_lshl_add_u64 v[160:161], s[20:21], 0, v[144:145]
	s_add_i32 m0, s19, 0xc000
	s_nop 0
	global_load_lds_dwordx4 v[160:161], off
	v_lshl_add_u64 v[160:161], s[20:21], 0, v[146:147]
	s_add_i32 m0, s19, 0xe000
	s_nop 0
	global_load_lds_dwordx4 v[160:161], off
	ds_read_b128 v[196:199], v169
	ds_read_b128 v[200:203], v169 offset:1024
	ds_read_b128 v[204:207], v169 offset:2048
	ds_read_b128 v[208:211], v169 offset:3072
	ds_read_b128 v[212:215], v169 offset:4096
	ds_read_b128 v[216:219], v169 offset:5120
	ds_read_b128 v[220:223], v169 offset:6144
	ds_read_b128 v[224:227], v169 offset:7168
	s_waitcnt vmcnt(8)
	s_waitcnt lgkmcnt(0)
	s_barrier
	v_mfma_f32_16x16x32_bf16 v[124:127], v[128:131], v[196:199], v[124:127]
	v_mfma_f32_16x16x32_bf16 v[124:127], v[154:157], v[200:203], v[124:127]
	v_mfma_f32_16x16x32_bf16 v[120:123], v[176:179], v[200:203], v[120:123]
	v_mfma_f32_16x16x32_bf16 v[120:123], v[172:175], v[196:199], v[120:123]
	v_mfma_f32_16x16x32_bf16 v[116:119], v[180:183], v[196:199], v[116:119]
	v_mfma_f32_16x16x32_bf16 v[116:119], v[184:187], v[200:203], v[116:119]
	v_mfma_f32_16x16x32_bf16 v[112:115], v[192:195], v[200:203], v[112:115]
	v_mfma_f32_16x16x32_bf16 v[112:115], v[188:191], v[196:199], v[112:115]
	v_mfma_f32_16x16x32_bf16 v[96:99], v[188:191], v[204:207], v[96:99]
	v_mfma_f32_16x16x32_bf16 v[96:99], v[192:195], v[208:211], v[96:99]
	v_mfma_f32_16x16x32_bf16 v[100:103], v[184:187], v[208:211], v[100:103]
	v_mfma_f32_16x16x32_bf16 v[100:103], v[180:183], v[204:207], v[100:103]
	v_mfma_f32_16x16x32_bf16 v[104:107], v[172:175], v[204:207], v[104:107]
	v_mfma_f32_16x16x32_bf16 v[104:107], v[176:179], v[208:211], v[104:107]
	v_mfma_f32_16x16x32_bf16 v[108:111], v[154:157], v[208:211], v[108:111]
	v_mfma_f32_16x16x32_bf16 v[108:111], v[128:131], v[204:207], v[108:111]
	v_mfma_f32_16x16x32_bf16 v[92:95], v[128:131], v[212:215], v[92:95]
	v_mfma_f32_16x16x32_bf16 v[92:95], v[154:157], v[216:219], v[92:95]
	v_mfma_f32_16x16x32_bf16 v[88:91], v[176:179], v[216:219], v[88:91]
	v_mfma_f32_16x16x32_bf16 v[88:91], v[172:175], v[212:215], v[88:91]
	v_mfma_f32_16x16x32_bf16 v[84:87], v[180:183], v[212:215], v[84:87]
	v_mfma_f32_16x16x32_bf16 v[84:87], v[184:187], v[216:219], v[84:87]
	v_mfma_f32_16x16x32_bf16 v[80:83], v[192:195], v[216:219], v[80:83]
	v_mfma_f32_16x16x32_bf16 v[80:83], v[188:191], v[212:215], v[80:83]
	v_mfma_f32_16x16x32_bf16 v[64:67], v[188:191], v[220:223], v[64:67]
	v_mfma_f32_16x16x32_bf16 v[64:67], v[192:195], v[224:227], v[64:67]
	v_mfma_f32_16x16x32_bf16 v[68:71], v[184:187], v[224:227], v[68:71]
	v_mfma_f32_16x16x32_bf16 v[68:71], v[180:183], v[220:223], v[68:71]
	v_mfma_f32_16x16x32_bf16 v[72:75], v[172:175], v[220:223], v[72:75]
	v_mfma_f32_16x16x32_bf16 v[72:75], v[176:179], v[224:227], v[72:75]
	v_mfma_f32_16x16x32_bf16 v[76:79], v[154:157], v[224:227], v[76:79]
	v_mfma_f32_16x16x32_bf16 v[76:79], v[128:131], v[220:223], v[76:79]
	s_barrier
	s_add_i32 s20, s45, s30
	v_lshl_add_u64 v[160:161], s[24:25], 0, v[134:135]
	s_mov_b32 m0, s20
	v_lshl_add_u64 v[164:165], s[24:25], 0, v[138:139]
	global_load_lds_dwordx4 v[160:161], off
	s_add_i32 m0, s20, 0x2000
	s_add_u32 s20, s24, 0x100000
	s_addc_u32 s21, s25, 0
	s_add_i32 s55, s46, s30
	global_load_lds_dwordx4 v[164:165], off
	v_lshl_add_u64 v[196:197], s[20:21], 0, v[134:135]
	s_mov_b32 m0, s55
	v_lshl_add_u64 v[228:229], s[26:27], 0, v[132:133]
	global_load_lds_dwordx4 v[196:197], off
	v_lshl_add_u64 v[196:197], s[20:21], 0, v[138:139]
	s_add_i32 m0, s55, 0x2000
	v_lshl_add_u64 v[230:231], s[26:27], 0, v[136:137]
	global_load_lds_dwordx4 v[196:197], off
	s_mov_b32 m0, s19
	s_nop 0
	global_load_lds_dwordx4 v[228:229], off
	s_mov_b32 m0, s36
	s_nop 0
	global_load_lds_dwordx4 v[230:231], off
	ds_read_b128 v[196:199], v169 offset:16384
	ds_read_b128 v[200:203], v169 offset:17408
	ds_read_b128 v[204:207], v169 offset:18432
	ds_read_b128 v[208:211], v169 offset:19456
	ds_read_b128 v[212:215], v169 offset:20480
	ds_read_b128 v[216:219], v169 offset:21504
	ds_read_b128 v[220:223], v169 offset:22528
	ds_read_b128 v[224:227], v169 offset:23552
	s_waitcnt vmcnt(8)
	s_waitcnt lgkmcnt(0)
	s_barrier
	v_mfma_f32_16x16x32_bf16 v[60:63], v[128:131], v[196:199], v[60:63]
	v_mfma_f32_16x16x32_bf16 v[60:63], v[154:157], v[200:203], v[60:63]
	v_mfma_f32_16x16x32_bf16 v[56:59], v[176:179], v[200:203], v[56:59]
	v_mfma_f32_16x16x32_bf16 v[56:59], v[172:175], v[196:199], v[56:59]
	v_mfma_f32_16x16x32_bf16 v[52:55], v[180:183], v[196:199], v[52:55]
	v_mfma_f32_16x16x32_bf16 v[52:55], v[184:187], v[200:203], v[52:55]
	v_mfma_f32_16x16x32_bf16 v[48:51], v[192:195], v[200:203], v[48:51]
	v_mfma_f32_16x16x32_bf16 v[48:51], v[188:191], v[196:199], v[48:51]
	v_mfma_f32_16x16x32_bf16 v[32:35], v[188:191], v[204:207], v[32:35]
	v_mfma_f32_16x16x32_bf16 v[32:35], v[192:195], v[208:211], v[32:35]
	v_mfma_f32_16x16x32_bf16 v[36:39], v[184:187], v[208:211], v[36:39]
	v_mfma_f32_16x16x32_bf16 v[36:39], v[180:183], v[204:207], v[36:39]
	v_mfma_f32_16x16x32_bf16 v[40:43], v[172:175], v[204:207], v[40:43]
	v_mfma_f32_16x16x32_bf16 v[40:43], v[176:179], v[208:211], v[40:43]
	v_mfma_f32_16x16x32_bf16 v[44:47], v[154:157], v[208:211], v[44:47]
	v_mfma_f32_16x16x32_bf16 v[44:47], v[128:131], v[204:207], v[44:47]
	v_mfma_f32_16x16x32_bf16 v[28:31], v[128:131], v[212:215], v[28:31]
	v_mfma_f32_16x16x32_bf16 v[28:31], v[154:157], v[216:219], v[28:31]
	v_mfma_f32_16x16x32_bf16 v[24:27], v[176:179], v[216:219], v[24:27]
	v_mfma_f32_16x16x32_bf16 v[24:27], v[172:175], v[212:215], v[24:27]
	v_mfma_f32_16x16x32_bf16 v[20:23], v[180:183], v[212:215], v[20:23]
	v_mfma_f32_16x16x32_bf16 v[20:23], v[184:187], v[216:219], v[20:23]
	v_mfma_f32_16x16x32_bf16 v[16:19], v[192:195], v[216:219], v[16:19]
	v_mfma_f32_16x16x32_bf16 v[16:19], v[188:191], v[212:215], v[16:19]
	v_mfma_f32_16x16x32_bf16 v[0:3], v[188:191], v[220:223], v[0:3]
	v_mfma_f32_16x16x32_bf16 v[0:3], v[192:195], v[224:227], v[0:3]
	v_mfma_f32_16x16x32_bf16 v[4:7], v[184:187], v[224:227], v[4:7]
	v_mfma_f32_16x16x32_bf16 v[4:7], v[180:183], v[220:223], v[4:7]
	v_mfma_f32_16x16x32_bf16 v[8:11], v[172:175], v[220:223], v[8:11]
	v_mfma_f32_16x16x32_bf16 v[8:11], v[176:179], v[224:227], v[8:11]
	v_mfma_f32_16x16x32_bf16 v[12:15], v[154:157], v[224:227], v[12:15]
	v_mfma_f32_16x16x32_bf16 v[12:15], v[128:131], v[220:223], v[12:15]
	s_barrier
	s_add_i32 s55, 0, 0x18000
	v_add_u32_e32 v153, s55, v159
	s_add_i32 s56, 0, 0x1c000
	ds_read_b128 v[128:131], v153
	ds_read_b128 v[154:157], v153 offset:1024
	ds_read_b128 v[172:175], v153 offset:2048
	ds_read_b128 v[176:179], v153 offset:3072
	v_add_u32_e32 v153, s56, v159
	ds_read_b128 v[180:183], v153
	ds_read_b128 v[184:187], v153 offset:1024
	ds_read_b128 v[188:191], v153 offset:2048
	ds_read_b128 v[192:195], v153 offset:3072
	s_add_u32 s20, s26, 0x100000
	s_addc_u32 s21, s27, 0
	s_mov_b32 m0, s37
	v_lshl_add_u64 v[196:197], s[20:21], 0, v[132:133]
	global_load_lds_dwordx4 v[196:197], off
	v_lshl_add_u64 v[196:197], s[20:21], 0, v[136:137]
	s_mov_b32 m0, s38
	s_nop 0
	global_load_lds_dwordx4 v[196:197], off
	ds_read_b128 v[196:199], v169 offset:32768
	ds_read_b128 v[200:203], v169 offset:33792
	ds_read_b128 v[204:207], v169 offset:34816
	ds_read_b128 v[208:211], v169 offset:35840
	ds_read_b128 v[212:215], v169 offset:36864
	ds_read_b128 v[216:219], v169 offset:37888
	ds_read_b128 v[220:223], v169 offset:38912
	ds_read_b128 v[224:227], v169 offset:39936
	s_waitcnt vmcnt(8)
	s_waitcnt lgkmcnt(0)
	s_barrier
	v_mfma_f32_16x16x32_bf16 v[124:127], v[128:131], v[196:199], v[124:127]
	v_mfma_f32_16x16x32_bf16 v[124:127], v[154:157], v[200:203], v[124:127]
	v_mfma_f32_16x16x32_bf16 v[120:123], v[176:179], v[200:203], v[120:123]
	v_mfma_f32_16x16x32_bf16 v[120:123], v[172:175], v[196:199], v[120:123]
	v_mfma_f32_16x16x32_bf16 v[116:119], v[180:183], v[196:199], v[116:119]
	v_mfma_f32_16x16x32_bf16 v[116:119], v[184:187], v[200:203], v[116:119]
	v_mfma_f32_16x16x32_bf16 v[112:115], v[192:195], v[200:203], v[112:115]
	v_mfma_f32_16x16x32_bf16 v[112:115], v[188:191], v[196:199], v[112:115]
	v_mfma_f32_16x16x32_bf16 v[96:99], v[188:191], v[204:207], v[96:99]
	v_mfma_f32_16x16x32_bf16 v[96:99], v[192:195], v[208:211], v[96:99]
	v_mfma_f32_16x16x32_bf16 v[100:103], v[184:187], v[208:211], v[100:103]
	v_mfma_f32_16x16x32_bf16 v[100:103], v[180:183], v[204:207], v[100:103]
	v_mfma_f32_16x16x32_bf16 v[104:107], v[172:175], v[204:207], v[104:107]
	v_mfma_f32_16x16x32_bf16 v[104:107], v[176:179], v[208:211], v[104:107]
	v_mfma_f32_16x16x32_bf16 v[108:111], v[154:157], v[208:211], v[108:111]
	v_mfma_f32_16x16x32_bf16 v[108:111], v[128:131], v[204:207], v[108:111]
	v_mfma_f32_16x16x32_bf16 v[92:95], v[128:131], v[212:215], v[92:95]
	v_mfma_f32_16x16x32_bf16 v[92:95], v[154:157], v[216:219], v[92:95]
	v_mfma_f32_16x16x32_bf16 v[88:91], v[176:179], v[216:219], v[88:91]
	v_mfma_f32_16x16x32_bf16 v[88:91], v[172:175], v[212:215], v[88:91]
	v_mfma_f32_16x16x32_bf16 v[84:87], v[180:183], v[212:215], v[84:87]
	v_mfma_f32_16x16x32_bf16 v[84:87], v[184:187], v[216:219], v[84:87]
	v_mfma_f32_16x16x32_bf16 v[80:83], v[192:195], v[216:219], v[80:83]
	v_mfma_f32_16x16x32_bf16 v[80:83], v[188:191], v[212:215], v[80:83]
	v_mfma_f32_16x16x32_bf16 v[64:67], v[188:191], v[220:223], v[64:67]
	v_mfma_f32_16x16x32_bf16 v[64:67], v[192:195], v[224:227], v[64:67]
	v_mfma_f32_16x16x32_bf16 v[68:71], v[184:187], v[224:227], v[68:71]
	v_mfma_f32_16x16x32_bf16 v[68:71], v[180:183], v[220:223], v[68:71]
	v_mfma_f32_16x16x32_bf16 v[72:75], v[172:175], v[220:223], v[72:75]
	v_mfma_f32_16x16x32_bf16 v[72:75], v[176:179], v[224:227], v[72:75]
	v_mfma_f32_16x16x32_bf16 v[76:79], v[154:157], v[224:227], v[76:79]
	v_mfma_f32_16x16x32_bf16 v[76:79], v[128:131], v[220:223], v[76:79]
	s_barrier
	s_add_i32 s20, s55, s30
	v_lshl_add_u64 v[160:161], v[160:161], 0, s[8:9]
	s_mov_b32 m0, s20
	s_nop 0
	global_load_lds_dwordx4 v[160:161], off
	s_add_i32 m0, s20, 0x2000
	s_add_u32 s20, s24, 0x100800
	v_lshl_add_u64 v[160:161], v[164:165], 0, s[8:9]
	s_addc_u32 s21, s25, 0
	s_add_i32 s24, s56, s30
	global_load_lds_dwordx4 v[160:161], off
	v_lshl_add_u64 v[160:161], s[20:21], 0, v[134:135]
	s_mov_b32 m0, s24
	s_nop 0
	global_load_lds_dwordx4 v[160:161], off
	v_lshl_add_u64 v[160:161], s[20:21], 0, v[138:139]
	s_add_i32 m0, s24, 0x2000
	s_nop 0
	global_load_lds_dwordx4 v[160:161], off
	v_lshl_add_u64 v[160:161], v[228:229], 0, s[8:9]
	s_mov_b32 m0, s41
	s_nop 0
	global_load_lds_dwordx4 v[160:161], off
	v_lshl_add_u64 v[160:161], v[230:231], 0, s[8:9]
	s_mov_b32 m0, s42
	s_nop 0
	global_load_lds_dwordx4 v[160:161], off
	ds_read_b128 v[196:199], v169 offset:49152
	ds_read_b128 v[200:203], v169 offset:50176
	ds_read_b128 v[204:207], v169 offset:51200
	ds_read_b128 v[208:211], v169 offset:52224
	ds_read_b128 v[212:215], v169 offset:53248
	ds_read_b128 v[216:219], v169 offset:54272
	ds_read_b128 v[220:223], v169 offset:55296
	ds_read_b128 v[224:227], v169 offset:56320
	s_waitcnt vmcnt(8)
	s_waitcnt lgkmcnt(0)
	s_barrier
	v_mfma_f32_16x16x32_bf16 v[60:63], v[128:131], v[196:199], v[60:63]
	v_mfma_f32_16x16x32_bf16 v[60:63], v[154:157], v[200:203], v[60:63]
	v_mfma_f32_16x16x32_bf16 v[56:59], v[176:179], v[200:203], v[56:59]
	v_mfma_f32_16x16x32_bf16 v[56:59], v[172:175], v[196:199], v[56:59]
	v_mfma_f32_16x16x32_bf16 v[52:55], v[180:183], v[196:199], v[52:55]
	v_mfma_f32_16x16x32_bf16 v[52:55], v[184:187], v[200:203], v[52:55]
	v_mfma_f32_16x16x32_bf16 v[48:51], v[192:195], v[200:203], v[48:51]
	v_mfma_f32_16x16x32_bf16 v[48:51], v[188:191], v[196:199], v[48:51]
	v_mfma_f32_16x16x32_bf16 v[32:35], v[188:191], v[204:207], v[32:35]
	v_mfma_f32_16x16x32_bf16 v[32:35], v[192:195], v[208:211], v[32:35]
	v_mfma_f32_16x16x32_bf16 v[36:39], v[184:187], v[208:211], v[36:39]
	v_mfma_f32_16x16x32_bf16 v[36:39], v[180:183], v[204:207], v[36:39]
	v_mfma_f32_16x16x32_bf16 v[40:43], v[172:175], v[204:207], v[40:43]
	v_mfma_f32_16x16x32_bf16 v[40:43], v[176:179], v[208:211], v[40:43]
	v_mfma_f32_16x16x32_bf16 v[44:47], v[154:157], v[208:211], v[44:47]
	v_mfma_f32_16x16x32_bf16 v[44:47], v[128:131], v[204:207], v[44:47]
	v_mfma_f32_16x16x32_bf16 v[28:31], v[128:131], v[212:215], v[28:31]
	v_mfma_f32_16x16x32_bf16 v[28:31], v[154:157], v[216:219], v[28:31]
	v_mfma_f32_16x16x32_bf16 v[24:27], v[176:179], v[216:219], v[24:27]
	v_mfma_f32_16x16x32_bf16 v[24:27], v[172:175], v[212:215], v[24:27]
	v_mfma_f32_16x16x32_bf16 v[20:23], v[180:183], v[212:215], v[20:23]
	v_mfma_f32_16x16x32_bf16 v[20:23], v[184:187], v[216:219], v[20:23]
	v_mfma_f32_16x16x32_bf16 v[16:19], v[192:195], v[216:219], v[16:19]
	v_mfma_f32_16x16x32_bf16 v[16:19], v[188:191], v[212:215], v[16:19]
	v_mfma_f32_16x16x32_bf16 v[0:3], v[188:191], v[220:223], v[0:3]
	v_mfma_f32_16x16x32_bf16 v[0:3], v[192:195], v[224:227], v[0:3]
	v_mfma_f32_16x16x32_bf16 v[4:7], v[184:187], v[224:227], v[4:7]
	v_mfma_f32_16x16x32_bf16 v[4:7], v[180:183], v[220:223], v[4:7]
	v_mfma_f32_16x16x32_bf16 v[8:11], v[172:175], v[220:223], v[8:11]
	v_mfma_f32_16x16x32_bf16 v[8:11], v[176:179], v[224:227], v[8:11]
	v_mfma_f32_16x16x32_bf16 v[12:15], v[154:157], v[224:227], v[12:15]
	v_mfma_f32_16x16x32_bf16 v[12:15], v[128:131], v[220:223], v[12:15]
	s_barrier
	s_add_i32 s54, s54, 2
	s_add_u32 s52, s52, 0x1000
	s_addc_u32 s53, s53, 0
	s_cmp_gt_u32 s54, 61
	s_mov_b64 s[20:21], s[22:23]
	s_cbranch_scc0 .LBB0_1543

.LBB0_1625:
	ds_read_b128 v[128:131], v177
	ds_read_b128 v[132:135], v177 offset:1024
	ds_read_b128 v[136:139], v177 offset:2048
	ds_read_b128 v[140:143], v177 offset:3072
	ds_read_b128 v[144:147], v178
	ds_read_b128 v[148:151], v178 offset:1024
	ds_read_b128 v[170:173], v178 offset:2048
	ds_read_b128 v[182:185], v178 offset:3072
	s_add_u32 s24, s22, 0xffc00800
	s_addc_u32 s25, s23, -1
	s_cmpk_eq_i32 s57, 0xfc
	s_cselect_b32 s27, s29, s25
	s_cselect_b32 s26, s53, s24
	s_cselect_b32 s25, s17, s56
	s_cselect_b32 s24, s54, s55
	v_lshl_add_u64 v[186:187], s[22:23], 0, v[162:163]
	s_add_i32 m0, s38, 0xc000
	s_nop 0
	global_load_lds_dwordx4 v[186:187], off
	v_lshl_add_u64 v[186:187], s[22:23], 0, v[164:165]
	s_add_i32 m0, s38, 0xe000
	s_nop 0
	global_load_lds_dwordx4 v[186:187], off
	ds_read_b128 v[186:189], v179
	ds_read_b128 v[190:193], v179 offset:1024
	ds_read_b128 v[194:197], v179 offset:2048
	ds_read_b128 v[198:201], v179 offset:3072
	ds_read_b128 v[202:205], v179 offset:4096
	ds_read_b128 v[206:209], v179 offset:5120
	ds_read_b128 v[210:213], v179 offset:6144
	ds_read_b128 v[214:217], v179 offset:7168
	s_waitcnt vmcnt(8)
	s_waitcnt lgkmcnt(0)
	s_barrier
	v_mfma_f32_16x16x32_bf16 v[124:127], v[128:131], v[186:189], v[124:127]
	v_mfma_f32_16x16x32_bf16 v[124:127], v[132:135], v[190:193], v[124:127]
	v_mfma_f32_16x16x32_bf16 v[120:123], v[140:143], v[190:193], v[120:123]
	v_mfma_f32_16x16x32_bf16 v[120:123], v[136:139], v[186:189], v[120:123]
	v_mfma_f32_16x16x32_bf16 v[116:119], v[144:147], v[186:189], v[116:119]
	v_mfma_f32_16x16x32_bf16 v[116:119], v[148:151], v[190:193], v[116:119]
	v_mfma_f32_16x16x32_bf16 v[112:115], v[182:185], v[190:193], v[112:115]
	v_mfma_f32_16x16x32_bf16 v[112:115], v[170:173], v[186:189], v[112:115]
	v_mfma_f32_16x16x32_bf16 v[96:99], v[170:173], v[194:197], v[96:99]
	v_mfma_f32_16x16x32_bf16 v[96:99], v[182:185], v[198:201], v[96:99]
	v_mfma_f32_16x16x32_bf16 v[100:103], v[148:151], v[198:201], v[100:103]
	v_mfma_f32_16x16x32_bf16 v[100:103], v[144:147], v[194:197], v[100:103]
	v_mfma_f32_16x16x32_bf16 v[104:107], v[136:139], v[194:197], v[104:107]
	v_mfma_f32_16x16x32_bf16 v[104:107], v[140:143], v[198:201], v[104:107]
	v_mfma_f32_16x16x32_bf16 v[108:111], v[132:135], v[198:201], v[108:111]
	v_mfma_f32_16x16x32_bf16 v[108:111], v[128:131], v[194:197], v[108:111]
	v_mfma_f32_16x16x32_bf16 v[92:95], v[128:131], v[202:205], v[92:95]
	v_mfma_f32_16x16x32_bf16 v[92:95], v[132:135], v[206:209], v[92:95]
	v_mfma_f32_16x16x32_bf16 v[88:91], v[140:143], v[206:209], v[88:91]
	v_mfma_f32_16x16x32_bf16 v[88:91], v[136:139], v[202:205], v[88:91]
	v_mfma_f32_16x16x32_bf16 v[84:87], v[144:147], v[202:205], v[84:87]
	v_mfma_f32_16x16x32_bf16 v[84:87], v[148:151], v[206:209], v[84:87]
	v_mfma_f32_16x16x32_bf16 v[80:83], v[182:185], v[206:209], v[80:83]
	v_mfma_f32_16x16x32_bf16 v[80:83], v[170:173], v[202:205], v[80:83]
	v_mfma_f32_16x16x32_bf16 v[64:67], v[170:173], v[210:213], v[64:67]
	v_mfma_f32_16x16x32_bf16 v[64:67], v[182:185], v[214:217], v[64:67]
	v_mfma_f32_16x16x32_bf16 v[68:71], v[148:151], v[214:217], v[68:71]
	v_mfma_f32_16x16x32_bf16 v[68:71], v[144:147], v[210:213], v[68:71]
	v_mfma_f32_16x16x32_bf16 v[72:75], v[136:139], v[210:213], v[72:75]
	v_mfma_f32_16x16x32_bf16 v[72:75], v[140:143], v[214:217], v[72:75]
	v_mfma_f32_16x16x32_bf16 v[76:79], v[132:135], v[214:217], v[76:79]
	v_mfma_f32_16x16x32_bf16 v[76:79], v[128:131], v[210:213], v[76:79]
	s_barrier
	s_add_i32 s58, s48, s37
	v_lshl_add_u64 v[218:219], s[24:25], 0, v[154:155]
	s_mov_b32 m0, s58
	v_lshl_add_u64 v[220:221], s[24:25], 0, v[158:159]
	global_load_lds_dwordx4 v[218:219], off
	s_add_i32 m0, s58, 0x2000
	s_add_u32 s58, s24, 0x400000
	s_addc_u32 s59, s25, 0
	s_add_i32 s60, s49, s37
	global_load_lds_dwordx4 v[220:221], off
	v_lshl_add_u64 v[186:187], s[58:59], 0, v[154:155]
	s_mov_b32 m0, s60
	v_lshl_add_u64 v[222:223], s[26:27], 0, v[152:153]
	global_load_lds_dwordx4 v[186:187], off
	v_lshl_add_u64 v[186:187], s[58:59], 0, v[158:159]
	s_add_i32 m0, s60, 0x2000
	v_lshl_add_u64 v[224:225], s[26:27], 0, v[156:157]
	global_load_lds_dwordx4 v[186:187], off
	s_mov_b32 m0, s38
	s_nop 0
	global_load_lds_dwordx4 v[222:223], off
	s_mov_b32 m0, s39
	s_nop 0
	global_load_lds_dwordx4 v[224:225], off
	ds_read_b128 v[186:189], v179 offset:16384
	ds_read_b128 v[190:193], v179 offset:17408
	ds_read_b128 v[194:197], v179 offset:18432
	ds_read_b128 v[198:201], v179 offset:19456
	ds_read_b128 v[202:205], v179 offset:20480
	ds_read_b128 v[206:209], v179 offset:21504
	ds_read_b128 v[210:213], v179 offset:22528
	ds_read_b128 v[214:217], v179 offset:23552
	s_waitcnt vmcnt(8)
	s_waitcnt lgkmcnt(0)
	s_barrier
	v_mfma_f32_16x16x32_bf16 v[60:63], v[128:131], v[186:189], v[60:63]
	v_mfma_f32_16x16x32_bf16 v[60:63], v[132:135], v[190:193], v[60:63]
	v_mfma_f32_16x16x32_bf16 v[56:59], v[140:143], v[190:193], v[56:59]
	v_mfma_f32_16x16x32_bf16 v[56:59], v[136:139], v[186:189], v[56:59]
	v_mfma_f32_16x16x32_bf16 v[52:55], v[144:147], v[186:189], v[52:55]
	v_mfma_f32_16x16x32_bf16 v[52:55], v[148:151], v[190:193], v[52:55]
	v_mfma_f32_16x16x32_bf16 v[48:51], v[182:185], v[190:193], v[48:51]
	v_mfma_f32_16x16x32_bf16 v[48:51], v[170:173], v[186:189], v[48:51]
	v_mfma_f32_16x16x32_bf16 v[32:35], v[170:173], v[194:197], v[32:35]
	v_mfma_f32_16x16x32_bf16 v[32:35], v[182:185], v[198:201], v[32:35]
	v_mfma_f32_16x16x32_bf16 v[36:39], v[148:151], v[198:201], v[36:39]
	v_mfma_f32_16x16x32_bf16 v[36:39], v[144:147], v[194:197], v[36:39]
	v_mfma_f32_16x16x32_bf16 v[40:43], v[136:139], v[194:197], v[40:43]
	v_mfma_f32_16x16x32_bf16 v[40:43], v[140:143], v[198:201], v[40:43]
	v_mfma_f32_16x16x32_bf16 v[44:47], v[132:135], v[198:201], v[44:47]
	v_mfma_f32_16x16x32_bf16 v[44:47], v[128:131], v[194:197], v[44:47]
	v_mfma_f32_16x16x32_bf16 v[28:31], v[128:131], v[202:205], v[28:31]
	v_mfma_f32_16x16x32_bf16 v[28:31], v[132:135], v[206:209], v[28:31]
	v_mfma_f32_16x16x32_bf16 v[24:27], v[140:143], v[206:209], v[24:27]
	v_mfma_f32_16x16x32_bf16 v[24:27], v[136:139], v[202:205], v[24:27]
	v_mfma_f32_16x16x32_bf16 v[20:23], v[144:147], v[202:205], v[20:23]
	v_mfma_f32_16x16x32_bf16 v[20:23], v[148:151], v[206:209], v[20:23]
	v_mfma_f32_16x16x32_bf16 v[16:19], v[182:185], v[206:209], v[16:19]
	v_mfma_f32_16x16x32_bf16 v[16:19], v[170:173], v[202:205], v[16:19]
	v_mfma_f32_16x16x32_bf16 v[0:3], v[170:173], v[210:213], v[0:3]
	v_mfma_f32_16x16x32_bf16 v[0:3], v[182:185], v[214:217], v[0:3]
	v_mfma_f32_16x16x32_bf16 v[4:7], v[148:151], v[214:217], v[4:7]
	v_mfma_f32_16x16x32_bf16 v[4:7], v[144:147], v[210:213], v[4:7]
	v_mfma_f32_16x16x32_bf16 v[8:11], v[136:139], v[210:213], v[8:11]
	v_mfma_f32_16x16x32_bf16 v[8:11], v[140:143], v[214:217], v[8:11]
	v_mfma_f32_16x16x32_bf16 v[12:15], v[132:135], v[214:217], v[12:15]
	v_mfma_f32_16x16x32_bf16 v[12:15], v[128:131], v[210:213], v[12:15]
	s_barrier
	s_add_i32 s58, 0, 0x18000
	s_add_i32 s59, 0, 0x1c000
	v_add_u32_e32 v140, s58, v174
	v_add_u32_e32 v181, s59, v174
	ds_read_b128 v[128:131], v140
	ds_read_b128 v[132:135], v140 offset:1024
	ds_read_b128 v[136:139], v140 offset:2048
	ds_read_b128 v[140:143], v140 offset:3072
	ds_read_b128 v[144:147], v181
	ds_read_b128 v[148:151], v181 offset:1024
	ds_read_b128 v[170:173], v181 offset:2048
	ds_read_b128 v[182:185], v181 offset:3072
	s_add_u32 s26, s26, 0x400000
	s_addc_u32 s27, s27, 0
	s_mov_b32 m0, s40
	v_lshl_add_u64 v[186:187], s[26:27], 0, v[152:153]
	global_load_lds_dwordx4 v[186:187], off
	v_lshl_add_u64 v[186:187], s[26:27], 0, v[156:157]
	s_mov_b32 m0, s41
	s_nop 0
	global_load_lds_dwordx4 v[186:187], off
	ds_read_b128 v[186:189], v179 offset:32768
	ds_read_b128 v[190:193], v179 offset:33792
	ds_read_b128 v[194:197], v179 offset:34816
	ds_read_b128 v[198:201], v179 offset:35840
	ds_read_b128 v[202:205], v179 offset:36864
	ds_read_b128 v[206:209], v179 offset:37888
	ds_read_b128 v[210:213], v179 offset:38912
	ds_read_b128 v[214:217], v179 offset:39936
	s_waitcnt vmcnt(8)
	s_waitcnt lgkmcnt(0)
	s_barrier
	v_mfma_f32_16x16x32_bf16 v[124:127], v[128:131], v[186:189], v[124:127]
	v_mfma_f32_16x16x32_bf16 v[124:127], v[132:135], v[190:193], v[124:127]
	v_mfma_f32_16x16x32_bf16 v[120:123], v[140:143], v[190:193], v[120:123]
	v_mfma_f32_16x16x32_bf16 v[120:123], v[136:139], v[186:189], v[120:123]
	v_mfma_f32_16x16x32_bf16 v[116:119], v[144:147], v[186:189], v[116:119]
	v_mfma_f32_16x16x32_bf16 v[116:119], v[148:151], v[190:193], v[116:119]
	v_mfma_f32_16x16x32_bf16 v[112:115], v[182:185], v[190:193], v[112:115]
	v_mfma_f32_16x16x32_bf16 v[112:115], v[170:173], v[186:189], v[112:115]
	v_mfma_f32_16x16x32_bf16 v[96:99], v[170:173], v[194:197], v[96:99]
	v_mfma_f32_16x16x32_bf16 v[96:99], v[182:185], v[198:201], v[96:99]
	v_mfma_f32_16x16x32_bf16 v[100:103], v[148:151], v[198:201], v[100:103]
	v_mfma_f32_16x16x32_bf16 v[100:103], v[144:147], v[194:197], v[100:103]
	v_mfma_f32_16x16x32_bf16 v[104:107], v[136:139], v[194:197], v[104:107]
	v_mfma_f32_16x16x32_bf16 v[104:107], v[140:143], v[198:201], v[104:107]
	v_mfma_f32_16x16x32_bf16 v[108:111], v[132:135], v[198:201], v[108:111]
	v_mfma_f32_16x16x32_bf16 v[108:111], v[128:131], v[194:197], v[108:111]
	v_mfma_f32_16x16x32_bf16 v[92:95], v[128:131], v[202:205], v[92:95]
	v_mfma_f32_16x16x32_bf16 v[92:95], v[132:135], v[206:209], v[92:95]
	v_mfma_f32_16x16x32_bf16 v[88:91], v[140:143], v[206:209], v[88:91]
	v_mfma_f32_16x16x32_bf16 v[88:91], v[136:139], v[202:205], v[88:91]
	v_mfma_f32_16x16x32_bf16 v[84:87], v[144:147], v[202:205], v[84:87]
	v_mfma_f32_16x16x32_bf16 v[84:87], v[148:151], v[206:209], v[84:87]
	v_mfma_f32_16x16x32_bf16 v[80:83], v[182:185], v[206:209], v[80:83]
	v_mfma_f32_16x16x32_bf16 v[80:83], v[170:173], v[202:205], v[80:83]
	v_mfma_f32_16x16x32_bf16 v[64:67], v[170:173], v[210:213], v[64:67]
	v_mfma_f32_16x16x32_bf16 v[64:67], v[182:185], v[214:217], v[64:67]
	v_mfma_f32_16x16x32_bf16 v[68:71], v[148:151], v[214:217], v[68:71]
	v_mfma_f32_16x16x32_bf16 v[68:71], v[144:147], v[210:213], v[68:71]
	v_mfma_f32_16x16x32_bf16 v[72:75], v[136:139], v[210:213], v[72:75]
	v_mfma_f32_16x16x32_bf16 v[72:75], v[140:143], v[214:217], v[72:75]
	v_mfma_f32_16x16x32_bf16 v[76:79], v[132:135], v[214:217], v[76:79]
	v_mfma_f32_16x16x32_bf16 v[76:79], v[128:131], v[210:213], v[76:79]
	s_barrier
	s_add_i32 s26, s58, s37
	v_lshl_add_u64 v[186:187], v[218:219], 0, s[14:15]
	s_mov_b32 m0, s26
	s_nop 0
	global_load_lds_dwordx4 v[186:187], off
	s_add_i32 m0, s26, 0x2000
	s_add_u32 s24, s24, 0x400800
	v_lshl_add_u64 v[186:187], v[220:221], 0, s[14:15]
	s_addc_u32 s25, s25, 0
	s_add_i32 s26, s59, s37
	global_load_lds_dwordx4 v[186:187], off
	v_lshl_add_u64 v[186:187], s[24:25], 0, v[154:155]
	s_mov_b32 m0, s26
	s_nop 0
	global_load_lds_dwordx4 v[186:187], off
	v_lshl_add_u64 v[186:187], s[24:25], 0, v[158:159]
	s_add_i32 m0, s26, 0x2000
	s_nop 0
	global_load_lds_dwordx4 v[186:187], off
	v_lshl_add_u64 v[186:187], v[222:223], 0, s[14:15]
	s_mov_b32 m0, s43
	s_nop 0
	global_load_lds_dwordx4 v[186:187], off
	v_lshl_add_u64 v[186:187], v[224:225], 0, s[14:15]
	s_mov_b32 m0, s44
	s_nop 0
	global_load_lds_dwordx4 v[186:187], off
	ds_read_b128 v[186:189], v179 offset:49152
	ds_read_b128 v[190:193], v179 offset:50176
	ds_read_b128 v[194:197], v179 offset:51200
	ds_read_b128 v[198:201], v179 offset:52224
	ds_read_b128 v[202:205], v179 offset:53248
	ds_read_b128 v[206:209], v179 offset:54272
	ds_read_b128 v[210:213], v179 offset:55296
	ds_read_b128 v[214:217], v179 offset:56320
	s_waitcnt vmcnt(8)
	s_waitcnt lgkmcnt(0)
	s_barrier
	v_mfma_f32_16x16x32_bf16 v[60:63], v[128:131], v[186:189], v[60:63]
	v_mfma_f32_16x16x32_bf16 v[60:63], v[132:135], v[190:193], v[60:63]
	v_mfma_f32_16x16x32_bf16 v[56:59], v[140:143], v[190:193], v[56:59]
	v_mfma_f32_16x16x32_bf16 v[56:59], v[136:139], v[186:189], v[56:59]
	v_mfma_f32_16x16x32_bf16 v[52:55], v[144:147], v[186:189], v[52:55]
	v_mfma_f32_16x16x32_bf16 v[52:55], v[148:151], v[190:193], v[52:55]
	v_mfma_f32_16x16x32_bf16 v[48:51], v[182:185], v[190:193], v[48:51]
	v_mfma_f32_16x16x32_bf16 v[48:51], v[170:173], v[186:189], v[48:51]
	v_mfma_f32_16x16x32_bf16 v[32:35], v[170:173], v[194:197], v[32:35]
	v_mfma_f32_16x16x32_bf16 v[32:35], v[182:185], v[198:201], v[32:35]
	v_mfma_f32_16x16x32_bf16 v[36:39], v[148:151], v[198:201], v[36:39]
	v_mfma_f32_16x16x32_bf16 v[36:39], v[144:147], v[194:197], v[36:39]
	v_mfma_f32_16x16x32_bf16 v[40:43], v[136:139], v[194:197], v[40:43]
	v_mfma_f32_16x16x32_bf16 v[40:43], v[140:143], v[198:201], v[40:43]
	v_mfma_f32_16x16x32_bf16 v[44:47], v[132:135], v[198:201], v[44:47]
	v_mfma_f32_16x16x32_bf16 v[44:47], v[128:131], v[194:197], v[44:47]
	v_mfma_f32_16x16x32_bf16 v[28:31], v[128:131], v[202:205], v[28:31]
	v_mfma_f32_16x16x32_bf16 v[28:31], v[132:135], v[206:209], v[28:31]
	v_mfma_f32_16x16x32_bf16 v[24:27], v[140:143], v[206:209], v[24:27]
	v_mfma_f32_16x16x32_bf16 v[24:27], v[136:139], v[202:205], v[24:27]
	v_mfma_f32_16x16x32_bf16 v[20:23], v[144:147], v[202:205], v[20:23]
	v_mfma_f32_16x16x32_bf16 v[20:23], v[148:151], v[206:209], v[20:23]
	v_mfma_f32_16x16x32_bf16 v[16:19], v[182:185], v[206:209], v[16:19]
	v_mfma_f32_16x16x32_bf16 v[16:19], v[170:173], v[202:205], v[16:19]
	v_mfma_f32_16x16x32_bf16 v[0:3], v[170:173], v[210:213], v[0:3]
	v_mfma_f32_16x16x32_bf16 v[0:3], v[182:185], v[214:217], v[0:3]
	v_mfma_f32_16x16x32_bf16 v[4:7], v[148:151], v[214:217], v[4:7]
	v_mfma_f32_16x16x32_bf16 v[4:7], v[144:147], v[210:213], v[4:7]
	v_mfma_f32_16x16x32_bf16 v[8:11], v[136:139], v[210:213], v[8:11]
	v_mfma_f32_16x16x32_bf16 v[8:11], v[140:143], v[214:217], v[8:11]
	v_mfma_f32_16x16x32_bf16 v[12:15], v[132:135], v[214:217], v[12:15]
	v_mfma_f32_16x16x32_bf16 v[12:15], v[128:131], v[210:213], v[12:15]
	s_barrier
	s_add_i32 s57, s57, 2
	s_add_u32 s22, s22, 0x1000
	s_addc_u32 s23, s23, 0
	s_add_u32 s55, s55, 0x1000
	s_addc_u32 s56, s56, 0
	s_cmpk_gt_u32 s57, 0xfd
	s_cbranch_scc0 .LBB0_1625
